# lora: each step's two weight n-tiles go to LDS once per workgroup (LDS-DMA, three buffers, one barrier per step) and every wave reads its MFMA fragments from there
# speedup vs baseline: 1.0150x; 1.0030x over previous
; __device__ __forceinline__ void phase_lora(const Ctx& p, LAS unsigned char* lds) {
;     ...
;                 float m8[8], z[8];
; #pragma unroll
;                 for (int e = 0; e < 8; ++e) m8[e] = mu[c + e];
;                 zshift8(p, ZRW, row, 1536 + c, m8, z);
; #pragma unroll
;                 for (int e = 0; e < 8; ++e) z[e] = cq == 0 ? tanhf(z[e]) : (cq == 1 ? z[e] : sigmoidf_(z[e]));
;                 u32x4 w; w.x = pk2(z[0], z[1]); w.y = pk2(z[2], z[3]); w.z = pk2(z[4], z[5]); w.w = pk2(z[6], z[7]);
;                 *(LAS u32x4*)(X + tt * 264 + c) = w;
;             }
;         }
;         asm volatile("s_waitcnt lgkmcnt(0)" ::: "memory");
;         bf16x8 bx[8];
; #pragma unroll
;         for (int ks = 0; ks < 8; ++ks) bx[ks] = *(const LAS bf16x8*)(X + q * 264 + ks * 32 + 8 * g);
;         const int row = r0 + q;
;         struct WF { bf16x8 w[2], a[2], gq[4]; f32x4 w0, a0; };
;         auto ldw = [&](WF& f, int nt) {
;             const int n = nt * 16 + q, c = nt * 16 + 4 * g;
; #pragma unroll
;             for (int ks = 0; ks < 2; ++ks) { f.w[ks] = *(const bf16x8*)(w2T + n * 64 + ks * 32 + 8 * g); f.a[ks] = *(const bf16x8*)(a2T + n * 64 + ks * 32 + 8 * g); }
; #pragma unroll
;             for (int ks = 0; ks < 4; ++ks) f.gq[ks] = *(const bf16x8*)(g2T + n * 128 + ks * 32 + 8 * g);
;             f.w0 = *(const f32x4*)(p.in(18) + c); f.a0 = *(const f32x4*)(p.in(20) + c);
;         };
;         auto tile = [&](const WF& f, int nt) {
;             f32x4 aw = (f32x4){0.f, 0.f, 0.f, 0.f}, aa = aw, ag = aw;
; #pragma unroll
;             for (int ks = 0; ks < 2; ++ks) { aw = __builtin_amdgcn_mfma_f32_16x16x32_bf16(f.w[ks], bx[ks], aw, 0, 0, 0); aa = __builtin_amdgcn_mfma_f32_16x16x32_bf16(f.a[ks], bx[2 + ks], aa, 0, 0, 0); }
; #pragma unroll
;             for (int ks = 0; ks < 4; ++ks) ag = __builtin_amdgcn_mfma_f32_16x16x32_bf16(f.gq[ks], bx[4 + ks], ag, 0, 0, 0);
;             const int c = nt * 16 + 4 * g;
;             f32x4 dec; float av[4];
; #pragma unroll
;             for (int e = 0; e < 4; ++e) {
;                 const float x = f.w0[e] + aw[e];
;                 const float sp = fmaxf(-x, 0.f) + log1pf(expf(-fabsf(x)));
;                 dec[e] = expf(-expf(-sp - 0.5f));
;                 av[e] = sigmoidf_(f.a0[e] + aa[e]);
;             }
;             *(f32x4*)(DEC + (size_t)row * 512 + c) = dec;
.Llora_nf7:
	v_sub_f32_e32 v152, v152, v144
	v_sub_f32_e32 v153, v153, v145
	v_sub_f32_e32 v154, v154, v146
	v_sub_f32_e32 v155, v155, v147
	v_sub_f32_e32 v156, v156, v148
	v_sub_f32_e32 v157, v157, v149
	v_sub_f32_e32 v158, v158, v150
	v_sub_f32_e32 v159, v159, v151
	v_fmac_f32_e32 v144, v152, v136
	v_fmac_f32_e32 v145, v153, v137
	v_fmac_f32_e32 v146, v154, v138
	v_fmac_f32_e32 v147, v155, v139
	v_fmac_f32_e32 v148, v156, v140
	v_fmac_f32_e32 v149, v157, v141
	v_fmac_f32_e32 v150, v158, v142
	v_fmac_f32_e32 v151, v159, v143
	v_mul_f32_e32 v152, v7, v144
	v_mul_f32_e32 v153, v7, v145
	v_mul_f32_e32 v154, v7, v146
	v_mul_f32_e32 v155, v7, v147
	v_mul_f32_e32 v156, v7, v148
	v_mul_f32_e32 v157, v7, v149
	v_mul_f32_e32 v158, v7, v150
	v_mul_f32_e32 v159, v7, v151
	v_exp_f32_e32 v152, v152
	v_exp_f32_e32 v153, v153
	v_exp_f32_e32 v154, v154
	v_exp_f32_e32 v155, v155
	v_exp_f32_e32 v156, v156
	v_exp_f32_e32 v157, v157
	v_exp_f32_e32 v158, v158
	v_exp_f32_e32 v159, v159
	v_add_f32_e32 v152, 1.0, v152
	v_add_f32_e32 v153, 1.0, v153
	v_add_f32_e32 v154, 1.0, v154
	v_add_f32_e32 v155, 1.0, v155
	v_add_f32_e32 v156, 1.0, v156
	v_add_f32_e32 v157, 1.0, v157
	v_add_f32_e32 v158, 1.0, v158
	v_add_f32_e32 v159, 1.0, v159
	v_rcp_f32_e32 v152, v152
	v_rcp_f32_e32 v153, v153
	v_rcp_f32_e32 v154, v154
	v_rcp_f32_e32 v155, v155
	v_rcp_f32_e32 v156, v156
	v_rcp_f32_e32 v157, v157
	v_rcp_f32_e32 v158, v158
	v_rcp_f32_e32 v159, v159
	v_fma_f32 v152, v152, v8, v9
	v_fma_f32 v153, v153, v8, v9
	v_fma_f32 v154, v154, v8, v9
	v_fma_f32 v155, v155, v8, v9
	v_fma_f32 v156, v156, v8, v9
	v_fma_f32 v157, v157, v8, v9
	v_fma_f32 v158, v158, v8, v9
	v_fma_f32 v159, v159, v8, v9
	v_cndmask_b32_e64 v152, v152, v144, s[48:49]
	v_cndmask_b32_e64 v153, v153, v145, s[48:49]
	v_cndmask_b32_e64 v154, v154, v146, s[48:49]
	v_cndmask_b32_e64 v155, v155, v147, s[48:49]
	v_cndmask_b32_e64 v156, v156, v148, s[48:49]
	v_cndmask_b32_e64 v157, v157, v149, s[48:49]
	v_cndmask_b32_e64 v158, v158, v150, s[48:49]
	v_cndmask_b32_e64 v159, v159, v151, s[48:49]
	v_cvt_pk_bf16_f32 v160, v152, v153
	v_cvt_pk_bf16_f32 v161, v154, v155
	v_cvt_pk_bf16_f32 v162, v156, v157
	v_cvt_pk_bf16_f32 v163, v158, v159
	ds_write_b128 v6, v[160:163] offset:112
	s_waitcnt lgkmcnt(0)
	ds_read_b128 v[184:187], v14 offset:0
	ds_read_b128 v[188:191], v14 offset:64
	ds_read_b128 v[192:195], v14 offset:128
	ds_read_b128 v[196:199], v14 offset:192
	ds_read_b128 v[200:203], v14 offset:256
	ds_read_b128 v[204:207], v14 offset:320
	ds_read_b128 v[208:211], v14 offset:384
	ds_read_b128 v[212:215], v14 offset:448
	s_lshl_b32 s2, s26, 4
	v_add_u32_e32 v137, s2, v10
	v_lshl_add_u32 v132, v11, 4, v10
	v_lshlrev_b32_e32 v132, 4, v132
	v_mov_b32_e32 v133, v132
	v_lshlrev_b32_e32 v134, 4, v11
	v_lshlrev_b32_e32 v135, 11, v137
	v_lshl_add_u32 v135, v11, 4, v135
	v_lshlrev_b32_e32 v136, 10, v137
	v_lshl_add_u32 v136, v11, 3, v136
	s_cmp_lg_u32 s57, 0
	s_cbranch_scc1 .Llora_single
	s_lshl_b32 s2, s56, 15
	v_add_u32_e32 v132, s2, v132
	s_lshl_b32 s2, s56, 16
	v_add_u32_e32 v133, s2, v133
	s_lshl_b32 s2, s56, 10
	v_add_u32_e32 v134, s2, v134
	v_add_u32_e32 v135, s2, v135
	s_lshl_b32 s2, s56, 9
	v_add_u32_e32 v136, s2, v136
	s_and_b32 s60, s27, 3
	s_cmp_gt_u32 s60, 1
	s_cselect_b32 s3, 1, 0
	s_movk_i32 s64, 0x800
	s_lshl_b32 s64, s64, s3
	s_lshl_b32 s2, s60, 16
	s_cmp_eq_u32 s60, 2
	s_cselect_b32 s2, 0x20000, s2
	s_cmp_eq_u32 s60, 3
	s_cselect_b32 s2, 0x20800, s2
	s_lshl_b32 s3, s64, 4
	s_mul_i32 s3, s3, s56
	s_add_u32 s2, s2, s3
	s_add_u32 s62, s24, s2
	s_addc_u32 s63, s25, 0
	s_lshl_b32 s2, s56, 13
	s_lshl_b32 s3, s60, 11
	s_add_i32 s2, s2, s3
	s_add_i32 s60, s2, 0x10800
	v_lshl_add_u32 v138, v11, 4, v10
	v_lshlrev_b32_e32 v138, 4, v138
	v_add_u32_e32 v139, 0x400, v138
	s_lshl_b32 s2, s56, 13
	v_add_u32_e32 v140, s2, v138
	v_add_u32_e32 v140, 0x10800, v140
	s_add_i32 m0, s60, 0x0
	s_nop 0
	global_load_lds_dwordx4 v138, s[62:63]
	s_add_i32 m0, s60, 0x400
	s_nop 0
	global_load_lds_dwordx4 v139, s[62:63]
	s_add_u32 s62, s62, s64
	s_addc_u32 s63, s63, 0
	s_add_i32 m0, s60, 0x4000
	s_nop 0
	global_load_lds_dwordx4 v138, s[62:63]
	s_add_i32 m0, s60, 0x4400
	s_nop 0
	global_load_lds_dwordx4 v139, s[62:63]
	s_add_u32 s62, s62, s64
	s_addc_u32 s63, s63, 0
	global_load_dwordx4 v[48:51], v134, s[20:21]
	global_load_dwordx4 v[52:55], v134, s[22:23]
	v_add_u32_e32 v134, 64, v134
	s_waitcnt vmcnt(4)
	s_barrier
; __device__ __forceinline__ unsigned pk2(float lo, float hi) { f32x2 v = {lo, hi}; bf16x2_t b = __builtin_convertvector(v, bf16x2_t); return __builtin_bit_cast(unsigned, b); }
; __device__ __forceinline__ float sigmoidf_(float x) { return frcp(1.f + fexp2(-1.4426950408889634f * x)); }
; __device__ __forceinline__ void phase_lora(const Ctx& p, LAS unsigned char* lds) {
;     ...
;         auto tile = [&](const WF& f, int nt) {
;             f32x4 aw = (f32x4){0.f, 0.f, 0.f, 0.f}, aa = aw, ag = aw;
; #pragma unroll
;             for (int ks = 0; ks < 2; ++ks) { aw = __builtin_amdgcn_mfma_f32_16x16x32_bf16(f.w[ks], bx[ks], aw, 0, 0, 0); aa = __builtin_amdgcn_mfma_f32_16x16x32_bf16(f.a[ks], bx[2 + ks], aa, 0, 0, 0); }
; #pragma unroll
;             for (int ks = 0; ks < 4; ++ks) ag = __builtin_amdgcn_mfma_f32_16x16x32_bf16(f.gq[ks], bx[4 + ks], ag, 0, 0, 0);
;             const int c = nt * 16 + 4 * g;
;             f32x4 dec; float av[4];
; #pragma unroll
;             for (int e = 0; e < 4; ++e) {
;                 const float x = f.w0[e] + aw[e];
;                 const float sp = fmaxf(-x, 0.f) + log1pf(expf(-fabsf(x)));
;                 dec[e] = expf(-expf(-sp - 0.5f));
;                 av[e] = sigmoidf_(f.a0[e] + aa[e]);
;             }
;             *(f32x4*)(DEC + (size_t)row * 512 + c) = dec;
;             *(u32x2*)(AB + (size_t)row * 512 + c) = (u32x2){pk2(av[0], av[1]), pk2(av[2], av[3])};
;             *(u32x2*)(GG + (size_t)row * 512 + c) = (u32x2){pk2(ag[0], ag[1]), pk2(ag[2], ag[3])};
;         };
;         WF fa, fb;
;         ldw(fa, 0);
; #pragma unroll 1
;         for (int nt = 0; nt < 32; nt += 2) {
;             ldw(fb, nt + 1);
;             tile(fa, nt);
;             ldw(fa, (nt + 2) & 31);
;             tile(fb, nt + 1);
	ds_read_b128 v[16:19], v140 offset:0
	ds_read_b128 v[20:23], v140 offset:1024
	ds_read_b128 v[24:27], v140 offset:2048
	ds_read_b128 v[28:31], v140 offset:3072
	ds_read_b128 v[32:35], v140 offset:4096
	ds_read_b128 v[36:39], v140 offset:5120
	ds_read_b128 v[40:43], v140 offset:6144
	ds_read_b128 v[44:47], v140 offset:7168
	s_add_i32 m0, s60, 0x8000
	s_nop 0
	global_load_lds_dwordx4 v138, s[62:63]
	s_add_i32 m0, s60, 0x8400
	s_nop 0
	global_load_lds_dwordx4 v139, s[62:63]
	s_add_u32 s62, s62, s64
	s_addc_u32 s63, s63, 0
	global_load_dwordx4 v[88:91], v134, s[20:21]
	global_load_dwordx4 v[92:95], v134, s[22:23]
	v_add_u32_e32 v134, 64, v134
	s_waitcnt vmcnt(4)
	s_waitcnt lgkmcnt(0)
	v_mfma_f32_16x16x32_bf16 v[96:99], v[16:19], v[184:187], 0
	v_mfma_f32_16x16x32_bf16 v[100:103], v[24:27], v[192:195], 0
	v_mfma_f32_16x16x32_bf16 v[104:107], v[32:35], v[200:203], 0
	v_mfma_f32_16x16x32_bf16 v[96:99], v[20:23], v[188:191], v[96:99]
	v_mfma_f32_16x16x32_bf16 v[100:103], v[28:31], v[196:199], v[100:103]
	v_mfma_f32_16x16x32_bf16 v[104:107], v[36:39], v[204:207], v[104:107]
	v_mfma_f32_16x16x32_bf16 v[104:107], v[40:43], v[208:211], v[104:107]
	v_mfma_f32_16x16x32_bf16 v[104:107], v[44:47], v[212:215], v[104:107]
	s_nop 4
	v_add_f32_e32 v108, v48, v96
	v_add_f32_e32 v109, v49, v97
	v_add_f32_e32 v110, v50, v98
	v_add_f32_e32 v111, v51, v99
	v_add_f32_e32 v112, v52, v100
	v_add_f32_e32 v113, v53, v101
	v_add_f32_e32 v114, v54, v102
	v_add_f32_e32 v115, v55, v103
	v_mul_f32_e32 v108, 0xbfb8aa3b, v108
	v_mul_f32_e32 v109, 0xbfb8aa3b, v109
	v_mul_f32_e32 v110, 0xbfb8aa3b, v110
	v_mul_f32_e32 v111, 0xbfb8aa3b, v111
	v_mul_f32_e32 v112, 0xbfb8aa3b, v112
	v_mul_f32_e32 v113, 0xbfb8aa3b, v113
	v_mul_f32_e32 v114, 0xbfb8aa3b, v114
	v_mul_f32_e32 v115, 0xbfb8aa3b, v115
	v_exp_f32_e32 v108, v108
	v_exp_f32_e32 v109, v109
	v_exp_f32_e32 v110, v110
	v_exp_f32_e32 v111, v111
	v_exp_f32_e32 v112, v112
	v_exp_f32_e32 v113, v113
	v_exp_f32_e32 v114, v114
	v_exp_f32_e32 v115, v115
	v_add_f32_e32 v108, 1.0, v108
	v_add_f32_e32 v109, 1.0, v109
	v_add_f32_e32 v110, 1.0, v110
	v_add_f32_e32 v111, 1.0, v111
	v_add_f32_e32 v112, 1.0, v112
	v_add_f32_e32 v113, 1.0, v113
	v_add_f32_e32 v114, 1.0, v114
	v_add_f32_e32 v115, 1.0, v115
	v_rcp_f32_e32 v108, v108
	v_rcp_f32_e32 v109, v109
	v_rcp_f32_e32 v110, v110
	v_rcp_f32_e32 v111, v111
	v_rcp_f32_e32 v112, v112
	v_rcp_f32_e32 v113, v113
	v_rcp_f32_e32 v114, v114
	v_rcp_f32_e32 v115, v115
	v_mul_f32_e32 v108, 0xbf60028b, v108
	v_mul_f32_e32 v109, 0xbf60028b, v109
	v_mul_f32_e32 v110, 0xbf60028b, v110
	v_mul_f32_e32 v111, 0xbf60028b, v111
	v_cvt_pk_bf16_f32 v116, v112, v113
	v_cvt_pk_bf16_f32 v117, v114, v115
	v_exp_f32_e32 v108, v108
	v_exp_f32_e32 v109, v109
	v_exp_f32_e32 v110, v110
	v_exp_f32_e32 v111, v111
	v_cvt_pk_bf16_f32 v118, v104, v105
	v_cvt_pk_bf16_f32 v119, v106, v107
	global_store_dwordx2 v136, v[116:117], s[44:45]
	global_store_dwordx2 v136, v[118:119], s[46:47]
	global_store_dwordx4 v135, v[108:111], s[54:55]
	v_add_u32_e32 v136, 32, v136
	v_add_u32_e32 v135, 64, v135
	s_waitcnt vmcnt(9)
	s_barrier
	ds_read_b128 v[16:19], v140 offset:16384
	ds_read_b128 v[20:23], v140 offset:17408
	ds_read_b128 v[24:27], v140 offset:18432
	ds_read_b128 v[28:31], v140 offset:19456
	ds_read_b128 v[32:35], v140 offset:20480
	ds_read_b128 v[36:39], v140 offset:21504
	ds_read_b128 v[40:43], v140 offset:22528
	ds_read_b128 v[44:47], v140 offset:23552
	s_add_i32 m0, s60, 0x0
	s_nop 0
	global_load_lds_dwordx4 v138, s[62:63]
	s_add_i32 m0, s60, 0x400
	s_nop 0
	global_load_lds_dwordx4 v139, s[62:63]
	s_add_u32 s62, s62, s64
	s_addc_u32 s63, s63, 0
	global_load_dwordx4 v[48:51], v134, s[20:21]
	global_load_dwordx4 v[52:55], v134, s[22:23]
	v_add_u32_e32 v134, 64, v134
	s_waitcnt vmcnt(7)
	s_waitcnt lgkmcnt(0)
	v_mfma_f32_16x16x32_bf16 v[96:99], v[16:19], v[184:187], 0
	v_mfma_f32_16x16x32_bf16 v[100:103], v[24:27], v[192:195], 0
	v_mfma_f32_16x16x32_bf16 v[104:107], v[32:35], v[200:203], 0
	v_mfma_f32_16x16x32_bf16 v[96:99], v[20:23], v[188:191], v[96:99]
	v_mfma_f32_16x16x32_bf16 v[100:103], v[28:31], v[196:199], v[100:103]
	v_mfma_f32_16x16x32_bf16 v[104:107], v[36:39], v[204:207], v[104:107]
	v_mfma_f32_16x16x32_bf16 v[104:107], v[40:43], v[208:211], v[104:107]
	v_mfma_f32_16x16x32_bf16 v[104:107], v[44:47], v[212:215], v[104:107]
	s_nop 4
	v_add_f32_e32 v108, v88, v96
	v_add_f32_e32 v109, v89, v97
	v_add_f32_e32 v110, v90, v98
	v_add_f32_e32 v111, v91, v99
	v_add_f32_e32 v112, v92, v100
	v_add_f32_e32 v113, v93, v101
	v_add_f32_e32 v114, v94, v102
	v_add_f32_e32 v115, v95, v103
	v_mul_f32_e32 v108, 0xbfb8aa3b, v108
	v_mul_f32_e32 v109, 0xbfb8aa3b, v109
	v_mul_f32_e32 v110, 0xbfb8aa3b, v110
	v_mul_f32_e32 v111, 0xbfb8aa3b, v111
	v_mul_f32_e32 v112, 0xbfb8aa3b, v112
	v_mul_f32_e32 v113, 0xbfb8aa3b, v113
	v_mul_f32_e32 v114, 0xbfb8aa3b, v114
	v_mul_f32_e32 v115, 0xbfb8aa3b, v115
	v_exp_f32_e32 v108, v108
	v_exp_f32_e32 v109, v109
	v_exp_f32_e32 v110, v110
	v_exp_f32_e32 v111, v111
	v_exp_f32_e32 v112, v112
	v_exp_f32_e32 v113, v113
	v_exp_f32_e32 v114, v114
	v_exp_f32_e32 v115, v115
	v_add_f32_e32 v108, 1.0, v108
	v_add_f32_e32 v109, 1.0, v109
	v_add_f32_e32 v110, 1.0, v110
	v_add_f32_e32 v111, 1.0, v111
	v_add_f32_e32 v112, 1.0, v112
	v_add_f32_e32 v113, 1.0, v113
	v_add_f32_e32 v114, 1.0, v114
	v_add_f32_e32 v115, 1.0, v115
	v_rcp_f32_e32 v108, v108
	v_rcp_f32_e32 v109, v109
	v_rcp_f32_e32 v110, v110
	v_rcp_f32_e32 v111, v111
	v_rcp_f32_e32 v112, v112
	v_rcp_f32_e32 v113, v113
	v_rcp_f32_e32 v114, v114
	v_rcp_f32_e32 v115, v115
	v_mul_f32_e32 v108, 0xbf60028b, v108
	v_mul_f32_e32 v109, 0xbf60028b, v109
	v_mul_f32_e32 v110, 0xbf60028b, v110
	v_mul_f32_e32 v111, 0xbf60028b, v111
	v_cvt_pk_bf16_f32 v116, v112, v113
	v_cvt_pk_bf16_f32 v117, v114, v115
	v_exp_f32_e32 v108, v108
	v_exp_f32_e32 v109, v109
	v_exp_f32_e32 v110, v110
	v_exp_f32_e32 v111, v111
	v_cvt_pk_bf16_f32 v118, v104, v105
	v_cvt_pk_bf16_f32 v119, v106, v107
	global_store_dwordx2 v136, v[116:117], s[44:45]
	global_store_dwordx2 v136, v[118:119], s[46:47]
	global_store_dwordx4 v135, v[108:111], s[54:55]
	v_add_u32_e32 v136, 32, v136
	v_add_u32_e32 v135, 64, v135
	s_waitcnt vmcnt(12)
	s_barrier
; __device__ __forceinline__ unsigned pk2(float lo, float hi) { f32x2 v = {lo, hi}; bf16x2_t b = __builtin_convertvector(v, bf16x2_t); return __builtin_bit_cast(unsigned, b); }
; __device__ __forceinline__ float sigmoidf_(float x) { return frcp(1.f + fexp2(-1.4426950408889634f * x)); }
; __device__ __forceinline__ void phase_lora(const Ctx& p, LAS unsigned char* lds) {
;     ...
;         auto tile = [&](const WF& f, int nt) {
;             f32x4 aw = (f32x4){0.f, 0.f, 0.f, 0.f}, aa = aw, ag = aw;
; #pragma unroll
;             for (int ks = 0; ks < 2; ++ks) { aw = __builtin_amdgcn_mfma_f32_16x16x32_bf16(f.w[ks], bx[ks], aw, 0, 0, 0); aa = __builtin_amdgcn_mfma_f32_16x16x32_bf16(f.a[ks], bx[2 + ks], aa, 0, 0, 0); }
; #pragma unroll
;             for (int ks = 0; ks < 4; ++ks) ag = __builtin_amdgcn_mfma_f32_16x16x32_bf16(f.gq[ks], bx[4 + ks], ag, 0, 0, 0);
;             const int c = nt * 16 + 4 * g;
;             f32x4 dec; float av[4];
; #pragma unroll
;             for (int e = 0; e < 4; ++e) {
;                 const float x = f.w0[e] + aw[e];
;                 const float sp = fmaxf(-x, 0.f) + log1pf(expf(-fabsf(x)));
;                 dec[e] = expf(-expf(-sp - 0.5f));
;                 av[e] = sigmoidf_(f.a0[e] + aa[e]);
;             }
;             *(f32x4*)(DEC + (size_t)row * 512 + c) = dec;
;             *(u32x2*)(AB + (size_t)row * 512 + c) = (u32x2){pk2(av[0], av[1]), pk2(av[2], av[3])};
;             *(u32x2*)(GG + (size_t)row * 512 + c) = (u32x2){pk2(ag[0], ag[1]), pk2(ag[2], ag[3])};
;         };
;         WF fa, fb;
;         ldw(fa, 0);
; #pragma unroll 1
;         for (int nt = 0; nt < 32; nt += 2) {
;             ldw(fb, nt + 1);
;             tile(fa, nt);
;             ldw(fa, (nt + 2) & 31);
;             tile(fb, nt + 1);
	ds_read_b128 v[16:19], v140 offset:32768
	ds_read_b128 v[20:23], v140 offset:33792
	ds_read_b128 v[24:27], v140 offset:34816
	ds_read_b128 v[28:31], v140 offset:35840
	ds_read_b128 v[32:35], v140 offset:36864
	ds_read_b128 v[36:39], v140 offset:37888
	ds_read_b128 v[40:43], v140 offset:38912
	ds_read_b128 v[44:47], v140 offset:39936
	s_add_i32 m0, s60, 0x4000
	s_nop 0
	global_load_lds_dwordx4 v138, s[62:63]
	s_add_i32 m0, s60, 0x4400
	s_nop 0
	global_load_lds_dwordx4 v139, s[62:63]
	s_add_u32 s62, s62, s64
	s_addc_u32 s63, s63, 0
	global_load_dwordx4 v[88:91], v134, s[20:21]
	global_load_dwordx4 v[92:95], v134, s[22:23]
	v_add_u32_e32 v134, 64, v134
	s_waitcnt vmcnt(7)
	s_waitcnt lgkmcnt(0)
	v_mfma_f32_16x16x32_bf16 v[96:99], v[16:19], v[184:187], 0
	v_mfma_f32_16x16x32_bf16 v[100:103], v[24:27], v[192:195], 0
	v_mfma_f32_16x16x32_bf16 v[104:107], v[32:35], v[200:203], 0
	v_mfma_f32_16x16x32_bf16 v[96:99], v[20:23], v[188:191], v[96:99]
	v_mfma_f32_16x16x32_bf16 v[100:103], v[28:31], v[196:199], v[100:103]
	v_mfma_f32_16x16x32_bf16 v[104:107], v[36:39], v[204:207], v[104:107]
	v_mfma_f32_16x16x32_bf16 v[104:107], v[40:43], v[208:211], v[104:107]
	v_mfma_f32_16x16x32_bf16 v[104:107], v[44:47], v[212:215], v[104:107]
	s_nop 4
	v_add_f32_e32 v108, v48, v96
	v_add_f32_e32 v109, v49, v97
	v_add_f32_e32 v110, v50, v98
	v_add_f32_e32 v111, v51, v99
	v_add_f32_e32 v112, v52, v100
	v_add_f32_e32 v113, v53, v101
	v_add_f32_e32 v114, v54, v102
	v_add_f32_e32 v115, v55, v103
	v_mul_f32_e32 v108, 0xbfb8aa3b, v108
	v_mul_f32_e32 v109, 0xbfb8aa3b, v109
	v_mul_f32_e32 v110, 0xbfb8aa3b, v110
	v_mul_f32_e32 v111, 0xbfb8aa3b, v111
	v_mul_f32_e32 v112, 0xbfb8aa3b, v112
	v_mul_f32_e32 v113, 0xbfb8aa3b, v113
	v_mul_f32_e32 v114, 0xbfb8aa3b, v114
	v_mul_f32_e32 v115, 0xbfb8aa3b, v115
	v_exp_f32_e32 v108, v108
	v_exp_f32_e32 v109, v109
	v_exp_f32_e32 v110, v110
	v_exp_f32_e32 v111, v111
	v_exp_f32_e32 v112, v112
	v_exp_f32_e32 v113, v113
	v_exp_f32_e32 v114, v114
	v_exp_f32_e32 v115, v115
	v_add_f32_e32 v108, 1.0, v108
	v_add_f32_e32 v109, 1.0, v109
	v_add_f32_e32 v110, 1.0, v110
	v_add_f32_e32 v111, 1.0, v111
	v_add_f32_e32 v112, 1.0, v112
	v_add_f32_e32 v113, 1.0, v113
	v_add_f32_e32 v114, 1.0, v114
	v_add_f32_e32 v115, 1.0, v115
	v_rcp_f32_e32 v108, v108
	v_rcp_f32_e32 v109, v109
	v_rcp_f32_e32 v110, v110
	v_rcp_f32_e32 v111, v111
	v_rcp_f32_e32 v112, v112
	v_rcp_f32_e32 v113, v113
	v_rcp_f32_e32 v114, v114
	v_rcp_f32_e32 v115, v115
	v_mul_f32_e32 v108, 0xbf60028b, v108
	v_mul_f32_e32 v109, 0xbf60028b, v109
	v_mul_f32_e32 v110, 0xbf60028b, v110
	v_mul_f32_e32 v111, 0xbf60028b, v111
	v_cvt_pk_bf16_f32 v116, v112, v113
	v_cvt_pk_bf16_f32 v117, v114, v115
	v_exp_f32_e32 v108, v108
	v_exp_f32_e32 v109, v109
	v_exp_f32_e32 v110, v110
	v_exp_f32_e32 v111, v111
	v_cvt_pk_bf16_f32 v118, v104, v105
	v_cvt_pk_bf16_f32 v119, v106, v107
	global_store_dwordx2 v136, v[116:117], s[44:45]
	global_store_dwordx2 v136, v[118:119], s[46:47]
	global_store_dwordx4 v135, v[108:111], s[54:55]
	v_add_u32_e32 v136, 32, v136
	v_add_u32_e32 v135, 64, v135
	s_waitcnt vmcnt(12)
	s_barrier
	ds_read_b128 v[16:19], v140 offset:0
	ds_read_b128 v[20:23], v140 offset:1024
	ds_read_b128 v[24:27], v140 offset:2048
	ds_read_b128 v[28:31], v140 offset:3072
	ds_read_b128 v[32:35], v140 offset:4096
	ds_read_b128 v[36:39], v140 offset:5120
	ds_read_b128 v[40:43], v140 offset:6144
	ds_read_b128 v[44:47], v140 offset:7168
	s_add_i32 m0, s60, 0x8000
	s_nop 0
	global_load_lds_dwordx4 v138, s[62:63]
	s_add_i32 m0, s60, 0x8400
	s_nop 0
	global_load_lds_dwordx4 v139, s[62:63]
	s_add_u32 s62, s62, s64
	s_addc_u32 s63, s63, 0
	global_load_dwordx4 v[48:51], v134, s[20:21]
	global_load_dwordx4 v[52:55], v134, s[22:23]
	v_add_u32_e32 v134, 64, v134
	s_waitcnt vmcnt(7)
	s_waitcnt lgkmcnt(0)
	v_mfma_f32_16x16x32_bf16 v[96:99], v[16:19], v[184:187], 0
	v_mfma_f32_16x16x32_bf16 v[100:103], v[24:27], v[192:195], 0
	v_mfma_f32_16x16x32_bf16 v[104:107], v[32:35], v[200:203], 0
	v_mfma_f32_16x16x32_bf16 v[96:99], v[20:23], v[188:191], v[96:99]
	v_mfma_f32_16x16x32_bf16 v[100:103], v[28:31], v[196:199], v[100:103]
	v_mfma_f32_16x16x32_bf16 v[104:107], v[36:39], v[204:207], v[104:107]
	v_mfma_f32_16x16x32_bf16 v[104:107], v[40:43], v[208:211], v[104:107]
	v_mfma_f32_16x16x32_bf16 v[104:107], v[44:47], v[212:215], v[104:107]
	s_nop 4
	v_add_f32_e32 v108, v88, v96
	v_add_f32_e32 v109, v89, v97
	v_add_f32_e32 v110, v90, v98
	v_add_f32_e32 v111, v91, v99
	v_add_f32_e32 v112, v92, v100
	v_add_f32_e32 v113, v93, v101
	v_add_f32_e32 v114, v94, v102
	v_add_f32_e32 v115, v95, v103
	v_mul_f32_e32 v108, 0xbfb8aa3b, v108
	v_mul_f32_e32 v109, 0xbfb8aa3b, v109
	v_mul_f32_e32 v110, 0xbfb8aa3b, v110
	v_mul_f32_e32 v111, 0xbfb8aa3b, v111
	v_mul_f32_e32 v112, 0xbfb8aa3b, v112
	v_mul_f32_e32 v113, 0xbfb8aa3b, v113
	v_mul_f32_e32 v114, 0xbfb8aa3b, v114
	v_mul_f32_e32 v115, 0xbfb8aa3b, v115
	v_exp_f32_e32 v108, v108
	v_exp_f32_e32 v109, v109
	v_exp_f32_e32 v110, v110
	v_exp_f32_e32 v111, v111
	v_exp_f32_e32 v112, v112
	v_exp_f32_e32 v113, v113
	v_exp_f32_e32 v114, v114
	v_exp_f32_e32 v115, v115
	v_add_f32_e32 v108, 1.0, v108
	v_add_f32_e32 v109, 1.0, v109
	v_add_f32_e32 v110, 1.0, v110
	v_add_f32_e32 v111, 1.0, v111
	v_add_f32_e32 v112, 1.0, v112
	v_add_f32_e32 v113, 1.0, v113
	v_add_f32_e32 v114, 1.0, v114
	v_add_f32_e32 v115, 1.0, v115
	v_rcp_f32_e32 v108, v108
	v_rcp_f32_e32 v109, v109
	v_rcp_f32_e32 v110, v110
	v_rcp_f32_e32 v111, v111
	v_rcp_f32_e32 v112, v112
	v_rcp_f32_e32 v113, v113
	v_rcp_f32_e32 v114, v114
	v_rcp_f32_e32 v115, v115
	v_mul_f32_e32 v108, 0xbf60028b, v108
	v_mul_f32_e32 v109, 0xbf60028b, v109
	v_mul_f32_e32 v110, 0xbf60028b, v110
	v_mul_f32_e32 v111, 0xbf60028b, v111
	v_cvt_pk_bf16_f32 v116, v112, v113
	v_cvt_pk_bf16_f32 v117, v114, v115
	v_exp_f32_e32 v108, v108
	v_exp_f32_e32 v109, v109
	v_exp_f32_e32 v110, v110
	v_exp_f32_e32 v111, v111
	v_cvt_pk_bf16_f32 v118, v104, v105
	v_cvt_pk_bf16_f32 v119, v106, v107
	global_store_dwordx2 v136, v[116:117], s[44:45]
	global_store_dwordx2 v136, v[118:119], s[46:47]
	global_store_dwordx4 v135, v[108:111], s[54:55]
	v_add_u32_e32 v136, 32, v136
	v_add_u32_e32 v135, 64, v135
	s_waitcnt vmcnt(12)
	s_barrier
; __device__ __forceinline__ unsigned pk2(float lo, float hi) { f32x2 v = {lo, hi}; bf16x2_t b = __builtin_convertvector(v, bf16x2_t); return __builtin_bit_cast(unsigned, b); }
; __device__ __forceinline__ float sigmoidf_(float x) { return frcp(1.f + fexp2(-1.4426950408889634f * x)); }
; __device__ __forceinline__ void phase_lora(const Ctx& p, LAS unsigned char* lds) {
;     ...
;         auto tile = [&](const WF& f, int nt) {
;             f32x4 aw = (f32x4){0.f, 0.f, 0.f, 0.f}, aa = aw, ag = aw;
; #pragma unroll
;             for (int ks = 0; ks < 2; ++ks) { aw = __builtin_amdgcn_mfma_f32_16x16x32_bf16(f.w[ks], bx[ks], aw, 0, 0, 0); aa = __builtin_amdgcn_mfma_f32_16x16x32_bf16(f.a[ks], bx[2 + ks], aa, 0, 0, 0); }
; #pragma unroll
;             for (int ks = 0; ks < 4; ++ks) ag = __builtin_amdgcn_mfma_f32_16x16x32_bf16(f.gq[ks], bx[4 + ks], ag, 0, 0, 0);
;             const int c = nt * 16 + 4 * g;
;             f32x4 dec; float av[4];
; #pragma unroll
;             for (int e = 0; e < 4; ++e) {
;                 const float x = f.w0[e] + aw[e];
;                 const float sp = fmaxf(-x, 0.f) + log1pf(expf(-fabsf(x)));
;                 dec[e] = expf(-expf(-sp - 0.5f));
;                 av[e] = sigmoidf_(f.a0[e] + aa[e]);
;             }
;             *(f32x4*)(DEC + (size_t)row * 512 + c) = dec;
;             *(u32x2*)(AB + (size_t)row * 512 + c) = (u32x2){pk2(av[0], av[1]), pk2(av[2], av[3])};
;             *(u32x2*)(GG + (size_t)row * 512 + c) = (u32x2){pk2(ag[0], ag[1]), pk2(ag[2], ag[3])};
;         };
;         WF fa, fb;
;         ldw(fa, 0);
; #pragma unroll 1
;         for (int nt = 0; nt < 32; nt += 2) {
;             ldw(fb, nt + 1);
;             tile(fa, nt);
;             ldw(fa, (nt + 2) & 31);
;             tile(fb, nt + 1);
	ds_read_b128 v[16:19], v140 offset:16384
	ds_read_b128 v[20:23], v140 offset:17408
	ds_read_b128 v[24:27], v140 offset:18432
	ds_read_b128 v[28:31], v140 offset:19456
	ds_read_b128 v[32:35], v140 offset:20480
	ds_read_b128 v[36:39], v140 offset:21504
	ds_read_b128 v[40:43], v140 offset:22528
	ds_read_b128 v[44:47], v140 offset:23552
	s_add_i32 m0, s60, 0x0
	s_nop 0
	global_load_lds_dwordx4 v138, s[62:63]
	s_add_i32 m0, s60, 0x400
	s_nop 0
	global_load_lds_dwordx4 v139, s[62:63]
	s_add_u32 s62, s62, s64
	s_addc_u32 s63, s63, 0
	global_load_dwordx4 v[88:91], v134, s[20:21]
	global_load_dwordx4 v[92:95], v134, s[22:23]
	v_add_u32_e32 v134, 64, v134
	s_waitcnt vmcnt(7)
	s_waitcnt lgkmcnt(0)
	v_mfma_f32_16x16x32_bf16 v[96:99], v[16:19], v[184:187], 0
	v_mfma_f32_16x16x32_bf16 v[100:103], v[24:27], v[192:195], 0
	v_mfma_f32_16x16x32_bf16 v[104:107], v[32:35], v[200:203], 0
	v_mfma_f32_16x16x32_bf16 v[96:99], v[20:23], v[188:191], v[96:99]
	v_mfma_f32_16x16x32_bf16 v[100:103], v[28:31], v[196:199], v[100:103]
	v_mfma_f32_16x16x32_bf16 v[104:107], v[36:39], v[204:207], v[104:107]
	v_mfma_f32_16x16x32_bf16 v[104:107], v[40:43], v[208:211], v[104:107]
	v_mfma_f32_16x16x32_bf16 v[104:107], v[44:47], v[212:215], v[104:107]
	s_nop 4
	v_add_f32_e32 v108, v48, v96
	v_add_f32_e32 v109, v49, v97
	v_add_f32_e32 v110, v50, v98
	v_add_f32_e32 v111, v51, v99
	v_add_f32_e32 v112, v52, v100
	v_add_f32_e32 v113, v53, v101
	v_add_f32_e32 v114, v54, v102
	v_add_f32_e32 v115, v55, v103
	v_mul_f32_e32 v108, 0xbfb8aa3b, v108
	v_mul_f32_e32 v109, 0xbfb8aa3b, v109
	v_mul_f32_e32 v110, 0xbfb8aa3b, v110
	v_mul_f32_e32 v111, 0xbfb8aa3b, v111
	v_mul_f32_e32 v112, 0xbfb8aa3b, v112
	v_mul_f32_e32 v113, 0xbfb8aa3b, v113
	v_mul_f32_e32 v114, 0xbfb8aa3b, v114
	v_mul_f32_e32 v115, 0xbfb8aa3b, v115
	v_exp_f32_e32 v108, v108
	v_exp_f32_e32 v109, v109
	v_exp_f32_e32 v110, v110
	v_exp_f32_e32 v111, v111
	v_exp_f32_e32 v112, v112
	v_exp_f32_e32 v113, v113
	v_exp_f32_e32 v114, v114
	v_exp_f32_e32 v115, v115
	v_add_f32_e32 v108, 1.0, v108
	v_add_f32_e32 v109, 1.0, v109
	v_add_f32_e32 v110, 1.0, v110
	v_add_f32_e32 v111, 1.0, v111
	v_add_f32_e32 v112, 1.0, v112
	v_add_f32_e32 v113, 1.0, v113
	v_add_f32_e32 v114, 1.0, v114
	v_add_f32_e32 v115, 1.0, v115
	v_rcp_f32_e32 v108, v108
	v_rcp_f32_e32 v109, v109
	v_rcp_f32_e32 v110, v110
	v_rcp_f32_e32 v111, v111
	v_rcp_f32_e32 v112, v112
	v_rcp_f32_e32 v113, v113
	v_rcp_f32_e32 v114, v114
	v_rcp_f32_e32 v115, v115
	v_mul_f32_e32 v108, 0xbf60028b, v108
	v_mul_f32_e32 v109, 0xbf60028b, v109
	v_mul_f32_e32 v110, 0xbf60028b, v110
	v_mul_f32_e32 v111, 0xbf60028b, v111
	v_cvt_pk_bf16_f32 v116, v112, v113
	v_cvt_pk_bf16_f32 v117, v114, v115
	v_exp_f32_e32 v108, v108
	v_exp_f32_e32 v109, v109
	v_exp_f32_e32 v110, v110
	v_exp_f32_e32 v111, v111
	v_cvt_pk_bf16_f32 v118, v104, v105
	v_cvt_pk_bf16_f32 v119, v106, v107
	global_store_dwordx2 v136, v[116:117], s[44:45]
	global_store_dwordx2 v136, v[118:119], s[46:47]
	global_store_dwordx4 v135, v[108:111], s[54:55]
	v_add_u32_e32 v136, 32, v136
	v_add_u32_e32 v135, 64, v135
	s_waitcnt vmcnt(12)
	s_barrier
	ds_read_b128 v[16:19], v140 offset:32768
	ds_read_b128 v[20:23], v140 offset:33792
	ds_read_b128 v[24:27], v140 offset:34816
	ds_read_b128 v[28:31], v140 offset:35840
	ds_read_b128 v[32:35], v140 offset:36864
	ds_read_b128 v[36:39], v140 offset:37888
	ds_read_b128 v[40:43], v140 offset:38912
	ds_read_b128 v[44:47], v140 offset:39936
	s_add_i32 m0, s60, 0x4000
	s_nop 0
	global_load_lds_dwordx4 v138, s[62:63]
	s_add_i32 m0, s60, 0x4400
	s_nop 0
	global_load_lds_dwordx4 v139, s[62:63]
	s_add_u32 s62, s62, s64
	s_addc_u32 s63, s63, 0
	global_load_dwordx4 v[48:51], v134, s[20:21]
	global_load_dwordx4 v[52:55], v134, s[22:23]
	v_add_u32_e32 v134, 64, v134
	s_waitcnt vmcnt(7)
	s_waitcnt lgkmcnt(0)
	v_mfma_f32_16x16x32_bf16 v[96:99], v[16:19], v[184:187], 0
	v_mfma_f32_16x16x32_bf16 v[100:103], v[24:27], v[192:195], 0
	v_mfma_f32_16x16x32_bf16 v[104:107], v[32:35], v[200:203], 0
	v_mfma_f32_16x16x32_bf16 v[96:99], v[20:23], v[188:191], v[96:99]
	v_mfma_f32_16x16x32_bf16 v[100:103], v[28:31], v[196:199], v[100:103]
	v_mfma_f32_16x16x32_bf16 v[104:107], v[36:39], v[204:207], v[104:107]
	v_mfma_f32_16x16x32_bf16 v[104:107], v[40:43], v[208:211], v[104:107]
	v_mfma_f32_16x16x32_bf16 v[104:107], v[44:47], v[212:215], v[104:107]
	s_nop 4
	v_add_f32_e32 v108, v88, v96
	v_add_f32_e32 v109, v89, v97
	v_add_f32_e32 v110, v90, v98
	v_add_f32_e32 v111, v91, v99
	v_add_f32_e32 v112, v92, v100
	v_add_f32_e32 v113, v93, v101
	v_add_f32_e32 v114, v94, v102
	v_add_f32_e32 v115, v95, v103
	v_mul_f32_e32 v108, 0xbfb8aa3b, v108
	v_mul_f32_e32 v109, 0xbfb8aa3b, v109
	v_mul_f32_e32 v110, 0xbfb8aa3b, v110
	v_mul_f32_e32 v111, 0xbfb8aa3b, v111
	v_mul_f32_e32 v112, 0xbfb8aa3b, v112
	v_mul_f32_e32 v113, 0xbfb8aa3b, v113
	v_mul_f32_e32 v114, 0xbfb8aa3b, v114
	v_mul_f32_e32 v115, 0xbfb8aa3b, v115
	v_exp_f32_e32 v108, v108
	v_exp_f32_e32 v109, v109
	v_exp_f32_e32 v110, v110
	v_exp_f32_e32 v111, v111
	v_exp_f32_e32 v112, v112
	v_exp_f32_e32 v113, v113
	v_exp_f32_e32 v114, v114
	v_exp_f32_e32 v115, v115
	v_add_f32_e32 v108, 1.0, v108
	v_add_f32_e32 v109, 1.0, v109
	v_add_f32_e32 v110, 1.0, v110
	v_add_f32_e32 v111, 1.0, v111
	v_add_f32_e32 v112, 1.0, v112
	v_add_f32_e32 v113, 1.0, v113
	v_add_f32_e32 v114, 1.0, v114
	v_add_f32_e32 v115, 1.0, v115
	v_rcp_f32_e32 v108, v108
	v_rcp_f32_e32 v109, v109
	v_rcp_f32_e32 v110, v110
	v_rcp_f32_e32 v111, v111
	v_rcp_f32_e32 v112, v112
	v_rcp_f32_e32 v113, v113
	v_rcp_f32_e32 v114, v114
	v_rcp_f32_e32 v115, v115
	v_mul_f32_e32 v108, 0xbf60028b, v108
	v_mul_f32_e32 v109, 0xbf60028b, v109
	v_mul_f32_e32 v110, 0xbf60028b, v110
	v_mul_f32_e32 v111, 0xbf60028b, v111
	v_cvt_pk_bf16_f32 v116, v112, v113
	v_cvt_pk_bf16_f32 v117, v114, v115
	v_exp_f32_e32 v108, v108
	v_exp_f32_e32 v109, v109
	v_exp_f32_e32 v110, v110
	v_exp_f32_e32 v111, v111
	v_cvt_pk_bf16_f32 v118, v104, v105
	v_cvt_pk_bf16_f32 v119, v106, v107
	global_store_dwordx2 v136, v[116:117], s[44:45]
	global_store_dwordx2 v136, v[118:119], s[46:47]
	global_store_dwordx4 v135, v[108:111], s[54:55]
	v_add_u32_e32 v136, 32, v136
	v_add_u32_e32 v135, 64, v135
	s_waitcnt vmcnt(12)
	s_barrier
; __device__ __forceinline__ unsigned pk2(float lo, float hi) { f32x2 v = {lo, hi}; bf16x2_t b = __builtin_convertvector(v, bf16x2_t); return __builtin_bit_cast(unsigned, b); }
; __device__ __forceinline__ float sigmoidf_(float x) { return frcp(1.f + fexp2(-1.4426950408889634f * x)); }
; __device__ __forceinline__ void phase_lora(const Ctx& p, LAS unsigned char* lds) {
;     ...
;         auto tile = [&](const WF& f, int nt) {
;             f32x4 aw = (f32x4){0.f, 0.f, 0.f, 0.f}, aa = aw, ag = aw;
; #pragma unroll
;             for (int ks = 0; ks < 2; ++ks) { aw = __builtin_amdgcn_mfma_f32_16x16x32_bf16(f.w[ks], bx[ks], aw, 0, 0, 0); aa = __builtin_amdgcn_mfma_f32_16x16x32_bf16(f.a[ks], bx[2 + ks], aa, 0, 0, 0); }
; #pragma unroll
;             for (int ks = 0; ks < 4; ++ks) ag = __builtin_amdgcn_mfma_f32_16x16x32_bf16(f.gq[ks], bx[4 + ks], ag, 0, 0, 0);
;             const int c = nt * 16 + 4 * g;
;             f32x4 dec; float av[4];
; #pragma unroll
;             for (int e = 0; e < 4; ++e) {
;                 const float x = f.w0[e] + aw[e];
;                 const float sp = fmaxf(-x, 0.f) + log1pf(expf(-fabsf(x)));
;                 dec[e] = expf(-expf(-sp - 0.5f));
;                 av[e] = sigmoidf_(f.a0[e] + aa[e]);
;             }
;             *(f32x4*)(DEC + (size_t)row * 512 + c) = dec;
;             *(u32x2*)(AB + (size_t)row * 512 + c) = (u32x2){pk2(av[0], av[1]), pk2(av[2], av[3])};
;             *(u32x2*)(GG + (size_t)row * 512 + c) = (u32x2){pk2(ag[0], ag[1]), pk2(ag[2], ag[3])};
;         };
;         WF fa, fb;
;         ldw(fa, 0);
; #pragma unroll 1
;         for (int nt = 0; nt < 32; nt += 2) {
;             ldw(fb, nt + 1);
;             tile(fa, nt);
;             ldw(fa, (nt + 2) & 31);
;             tile(fb, nt + 1);
	ds_read_b128 v[16:19], v140 offset:0
	ds_read_b128 v[20:23], v140 offset:1024
	ds_read_b128 v[24:27], v140 offset:2048
	ds_read_b128 v[28:31], v140 offset:3072
	ds_read_b128 v[32:35], v140 offset:4096
	ds_read_b128 v[36:39], v140 offset:5120
	ds_read_b128 v[40:43], v140 offset:6144
	ds_read_b128 v[44:47], v140 offset:7168
	s_add_i32 m0, s60, 0x8000
	s_nop 0
	global_load_lds_dwordx4 v138, s[62:63]
	s_add_i32 m0, s60, 0x8400
	s_nop 0
	global_load_lds_dwordx4 v139, s[62:63]
	s_add_u32 s62, s62, s64
	s_addc_u32 s63, s63, 0
	global_load_dwordx4 v[88:91], v134, s[20:21]
	global_load_dwordx4 v[92:95], v134, s[22:23]
	v_add_u32_e32 v134, 64, v134
	s_waitcnt vmcnt(7)
	s_waitcnt lgkmcnt(0)
	v_mfma_f32_16x16x32_bf16 v[96:99], v[16:19], v[184:187], 0
	v_mfma_f32_16x16x32_bf16 v[100:103], v[24:27], v[192:195], 0
	v_mfma_f32_16x16x32_bf16 v[104:107], v[32:35], v[200:203], 0
	v_mfma_f32_16x16x32_bf16 v[96:99], v[20:23], v[188:191], v[96:99]
	v_mfma_f32_16x16x32_bf16 v[100:103], v[28:31], v[196:199], v[100:103]
	v_mfma_f32_16x16x32_bf16 v[104:107], v[36:39], v[204:207], v[104:107]
	v_mfma_f32_16x16x32_bf16 v[104:107], v[40:43], v[208:211], v[104:107]
	v_mfma_f32_16x16x32_bf16 v[104:107], v[44:47], v[212:215], v[104:107]
	s_nop 4
	v_add_f32_e32 v108, v48, v96
	v_add_f32_e32 v109, v49, v97
	v_add_f32_e32 v110, v50, v98
	v_add_f32_e32 v111, v51, v99
	v_add_f32_e32 v112, v52, v100
	v_add_f32_e32 v113, v53, v101
	v_add_f32_e32 v114, v54, v102
	v_add_f32_e32 v115, v55, v103
	v_mul_f32_e32 v108, 0xbfb8aa3b, v108
	v_mul_f32_e32 v109, 0xbfb8aa3b, v109
	v_mul_f32_e32 v110, 0xbfb8aa3b, v110
	v_mul_f32_e32 v111, 0xbfb8aa3b, v111
	v_mul_f32_e32 v112, 0xbfb8aa3b, v112
	v_mul_f32_e32 v113, 0xbfb8aa3b, v113
	v_mul_f32_e32 v114, 0xbfb8aa3b, v114
	v_mul_f32_e32 v115, 0xbfb8aa3b, v115
	v_exp_f32_e32 v108, v108
	v_exp_f32_e32 v109, v109
	v_exp_f32_e32 v110, v110
	v_exp_f32_e32 v111, v111
	v_exp_f32_e32 v112, v112
	v_exp_f32_e32 v113, v113
	v_exp_f32_e32 v114, v114
	v_exp_f32_e32 v115, v115
	v_add_f32_e32 v108, 1.0, v108
	v_add_f32_e32 v109, 1.0, v109
	v_add_f32_e32 v110, 1.0, v110
	v_add_f32_e32 v111, 1.0, v111
	v_add_f32_e32 v112, 1.0, v112
	v_add_f32_e32 v113, 1.0, v113
	v_add_f32_e32 v114, 1.0, v114
	v_add_f32_e32 v115, 1.0, v115
	v_rcp_f32_e32 v108, v108
	v_rcp_f32_e32 v109, v109
	v_rcp_f32_e32 v110, v110
	v_rcp_f32_e32 v111, v111
	v_rcp_f32_e32 v112, v112
	v_rcp_f32_e32 v113, v113
	v_rcp_f32_e32 v114, v114
	v_rcp_f32_e32 v115, v115
	v_mul_f32_e32 v108, 0xbf60028b, v108
	v_mul_f32_e32 v109, 0xbf60028b, v109
	v_mul_f32_e32 v110, 0xbf60028b, v110
	v_mul_f32_e32 v111, 0xbf60028b, v111
	v_cvt_pk_bf16_f32 v116, v112, v113
	v_cvt_pk_bf16_f32 v117, v114, v115
	v_exp_f32_e32 v108, v108
	v_exp_f32_e32 v109, v109
	v_exp_f32_e32 v110, v110
	v_exp_f32_e32 v111, v111
	v_cvt_pk_bf16_f32 v118, v104, v105
	v_cvt_pk_bf16_f32 v119, v106, v107
	global_store_dwordx2 v136, v[116:117], s[44:45]
	global_store_dwordx2 v136, v[118:119], s[46:47]
	global_store_dwordx4 v135, v[108:111], s[54:55]
	v_add_u32_e32 v136, 32, v136
	v_add_u32_e32 v135, 64, v135
	s_waitcnt vmcnt(12)
	s_barrier
	ds_read_b128 v[16:19], v140 offset:16384
	ds_read_b128 v[20:23], v140 offset:17408
	ds_read_b128 v[24:27], v140 offset:18432
	ds_read_b128 v[28:31], v140 offset:19456
	ds_read_b128 v[32:35], v140 offset:20480
	ds_read_b128 v[36:39], v140 offset:21504
	ds_read_b128 v[40:43], v140 offset:22528
	ds_read_b128 v[44:47], v140 offset:23552
	s_add_i32 m0, s60, 0x0
	s_nop 0
	global_load_lds_dwordx4 v138, s[62:63]
	s_add_i32 m0, s60, 0x400
	s_nop 0
	global_load_lds_dwordx4 v139, s[62:63]
	s_add_u32 s62, s62, s64
	s_addc_u32 s63, s63, 0
	global_load_dwordx4 v[48:51], v134, s[20:21]
	global_load_dwordx4 v[52:55], v134, s[22:23]
	v_add_u32_e32 v134, 64, v134
	s_waitcnt vmcnt(7)
	s_waitcnt lgkmcnt(0)
	v_mfma_f32_16x16x32_bf16 v[96:99], v[16:19], v[184:187], 0
	v_mfma_f32_16x16x32_bf16 v[100:103], v[24:27], v[192:195], 0
	v_mfma_f32_16x16x32_bf16 v[104:107], v[32:35], v[200:203], 0
	v_mfma_f32_16x16x32_bf16 v[96:99], v[20:23], v[188:191], v[96:99]
	v_mfma_f32_16x16x32_bf16 v[100:103], v[28:31], v[196:199], v[100:103]
	v_mfma_f32_16x16x32_bf16 v[104:107], v[36:39], v[204:207], v[104:107]
	v_mfma_f32_16x16x32_bf16 v[104:107], v[40:43], v[208:211], v[104:107]
	v_mfma_f32_16x16x32_bf16 v[104:107], v[44:47], v[212:215], v[104:107]
	s_nop 4
	v_add_f32_e32 v108, v88, v96
	v_add_f32_e32 v109, v89, v97
	v_add_f32_e32 v110, v90, v98
	v_add_f32_e32 v111, v91, v99
	v_add_f32_e32 v112, v92, v100
	v_add_f32_e32 v113, v93, v101
	v_add_f32_e32 v114, v94, v102
	v_add_f32_e32 v115, v95, v103
	v_mul_f32_e32 v108, 0xbfb8aa3b, v108
	v_mul_f32_e32 v109, 0xbfb8aa3b, v109
	v_mul_f32_e32 v110, 0xbfb8aa3b, v110
	v_mul_f32_e32 v111, 0xbfb8aa3b, v111
	v_mul_f32_e32 v112, 0xbfb8aa3b, v112
	v_mul_f32_e32 v113, 0xbfb8aa3b, v113
	v_mul_f32_e32 v114, 0xbfb8aa3b, v114
	v_mul_f32_e32 v115, 0xbfb8aa3b, v115
	v_exp_f32_e32 v108, v108
	v_exp_f32_e32 v109, v109
	v_exp_f32_e32 v110, v110
	v_exp_f32_e32 v111, v111
	v_exp_f32_e32 v112, v112
	v_exp_f32_e32 v113, v113
	v_exp_f32_e32 v114, v114
	v_exp_f32_e32 v115, v115
	v_add_f32_e32 v108, 1.0, v108
	v_add_f32_e32 v109, 1.0, v109
	v_add_f32_e32 v110, 1.0, v110
	v_add_f32_e32 v111, 1.0, v111
	v_add_f32_e32 v112, 1.0, v112
	v_add_f32_e32 v113, 1.0, v113
	v_add_f32_e32 v114, 1.0, v114
	v_add_f32_e32 v115, 1.0, v115
	v_rcp_f32_e32 v108, v108
	v_rcp_f32_e32 v109, v109
	v_rcp_f32_e32 v110, v110
	v_rcp_f32_e32 v111, v111
	v_rcp_f32_e32 v112, v112
	v_rcp_f32_e32 v113, v113
	v_rcp_f32_e32 v114, v114
	v_rcp_f32_e32 v115, v115
	v_mul_f32_e32 v108, 0xbf60028b, v108
	v_mul_f32_e32 v109, 0xbf60028b, v109
	v_mul_f32_e32 v110, 0xbf60028b, v110
	v_mul_f32_e32 v111, 0xbf60028b, v111
	v_cvt_pk_bf16_f32 v116, v112, v113
	v_cvt_pk_bf16_f32 v117, v114, v115
	v_exp_f32_e32 v108, v108
	v_exp_f32_e32 v109, v109
	v_exp_f32_e32 v110, v110
	v_exp_f32_e32 v111, v111
	v_cvt_pk_bf16_f32 v118, v104, v105
	v_cvt_pk_bf16_f32 v119, v106, v107
	global_store_dwordx2 v136, v[116:117], s[44:45]
	global_store_dwordx2 v136, v[118:119], s[46:47]
	global_store_dwordx4 v135, v[108:111], s[54:55]
	v_add_u32_e32 v136, 32, v136
	v_add_u32_e32 v135, 64, v135
	s_waitcnt vmcnt(12)
	s_barrier
; __device__ __forceinline__ unsigned pk2(float lo, float hi) { f32x2 v = {lo, hi}; bf16x2_t b = __builtin_convertvector(v, bf16x2_t); return __builtin_bit_cast(unsigned, b); }
; __device__ __forceinline__ float sigmoidf_(float x) { return frcp(1.f + fexp2(-1.4426950408889634f * x)); }
; __device__ __forceinline__ void phase_lora(const Ctx& p, LAS unsigned char* lds) {
;     ...
;         auto tile = [&](const WF& f, int nt) {
;             f32x4 aw = (f32x4){0.f, 0.f, 0.f, 0.f}, aa = aw, ag = aw;
; #pragma unroll
;             for (int ks = 0; ks < 2; ++ks) { aw = __builtin_amdgcn_mfma_f32_16x16x32_bf16(f.w[ks], bx[ks], aw, 0, 0, 0); aa = __builtin_amdgcn_mfma_f32_16x16x32_bf16(f.a[ks], bx[2 + ks], aa, 0, 0, 0); }
; #pragma unroll
;             for (int ks = 0; ks < 4; ++ks) ag = __builtin_amdgcn_mfma_f32_16x16x32_bf16(f.gq[ks], bx[4 + ks], ag, 0, 0, 0);
;             const int c = nt * 16 + 4 * g;
;             f32x4 dec; float av[4];
; #pragma unroll
;             for (int e = 0; e < 4; ++e) {
;                 const float x = f.w0[e] + aw[e];
;                 const float sp = fmaxf(-x, 0.f) + log1pf(expf(-fabsf(x)));
;                 dec[e] = expf(-expf(-sp - 0.5f));
;                 av[e] = sigmoidf_(f.a0[e] + aa[e]);
;             }
;             *(f32x4*)(DEC + (size_t)row * 512 + c) = dec;
;             *(u32x2*)(AB + (size_t)row * 512 + c) = (u32x2){pk2(av[0], av[1]), pk2(av[2], av[3])};
;             *(u32x2*)(GG + (size_t)row * 512 + c) = (u32x2){pk2(ag[0], ag[1]), pk2(ag[2], ag[3])};
;         };
;         WF fa, fb;
;         ldw(fa, 0);
; #pragma unroll 1
;         for (int nt = 0; nt < 32; nt += 2) {
;             ldw(fb, nt + 1);
;             tile(fa, nt);
;             ldw(fa, (nt + 2) & 31);
;             tile(fb, nt + 1);
	ds_read_b128 v[16:19], v140 offset:32768
	ds_read_b128 v[20:23], v140 offset:33792
	ds_read_b128 v[24:27], v140 offset:34816
	ds_read_b128 v[28:31], v140 offset:35840
	ds_read_b128 v[32:35], v140 offset:36864
	ds_read_b128 v[36:39], v140 offset:37888
	ds_read_b128 v[40:43], v140 offset:38912
	ds_read_b128 v[44:47], v140 offset:39936
	s_add_i32 m0, s60, 0x4000
	s_nop 0
	global_load_lds_dwordx4 v138, s[62:63]
	s_add_i32 m0, s60, 0x4400
	s_nop 0
	global_load_lds_dwordx4 v139, s[62:63]
	s_add_u32 s62, s62, s64
	s_addc_u32 s63, s63, 0
	global_load_dwordx4 v[88:91], v134, s[20:21]
	global_load_dwordx4 v[92:95], v134, s[22:23]
	v_add_u32_e32 v134, 64, v134
	s_waitcnt vmcnt(7)
	s_waitcnt lgkmcnt(0)
	v_mfma_f32_16x16x32_bf16 v[96:99], v[16:19], v[184:187], 0
	v_mfma_f32_16x16x32_bf16 v[100:103], v[24:27], v[192:195], 0
	v_mfma_f32_16x16x32_bf16 v[104:107], v[32:35], v[200:203], 0
	v_mfma_f32_16x16x32_bf16 v[96:99], v[20:23], v[188:191], v[96:99]
	v_mfma_f32_16x16x32_bf16 v[100:103], v[28:31], v[196:199], v[100:103]
	v_mfma_f32_16x16x32_bf16 v[104:107], v[36:39], v[204:207], v[104:107]
	v_mfma_f32_16x16x32_bf16 v[104:107], v[40:43], v[208:211], v[104:107]
	v_mfma_f32_16x16x32_bf16 v[104:107], v[44:47], v[212:215], v[104:107]
	s_nop 4
	v_add_f32_e32 v108, v48, v96
	v_add_f32_e32 v109, v49, v97
	v_add_f32_e32 v110, v50, v98
	v_add_f32_e32 v111, v51, v99
	v_add_f32_e32 v112, v52, v100
	v_add_f32_e32 v113, v53, v101
	v_add_f32_e32 v114, v54, v102
	v_add_f32_e32 v115, v55, v103
	v_mul_f32_e32 v108, 0xbfb8aa3b, v108
	v_mul_f32_e32 v109, 0xbfb8aa3b, v109
	v_mul_f32_e32 v110, 0xbfb8aa3b, v110
	v_mul_f32_e32 v111, 0xbfb8aa3b, v111
	v_mul_f32_e32 v112, 0xbfb8aa3b, v112
	v_mul_f32_e32 v113, 0xbfb8aa3b, v113
	v_mul_f32_e32 v114, 0xbfb8aa3b, v114
	v_mul_f32_e32 v115, 0xbfb8aa3b, v115
	v_exp_f32_e32 v108, v108
	v_exp_f32_e32 v109, v109
	v_exp_f32_e32 v110, v110
	v_exp_f32_e32 v111, v111
	v_exp_f32_e32 v112, v112
	v_exp_f32_e32 v113, v113
	v_exp_f32_e32 v114, v114
	v_exp_f32_e32 v115, v115
	v_add_f32_e32 v108, 1.0, v108
	v_add_f32_e32 v109, 1.0, v109
	v_add_f32_e32 v110, 1.0, v110
	v_add_f32_e32 v111, 1.0, v111
	v_add_f32_e32 v112, 1.0, v112
	v_add_f32_e32 v113, 1.0, v113
	v_add_f32_e32 v114, 1.0, v114
	v_add_f32_e32 v115, 1.0, v115
	v_rcp_f32_e32 v108, v108
	v_rcp_f32_e32 v109, v109
	v_rcp_f32_e32 v110, v110
	v_rcp_f32_e32 v111, v111
	v_rcp_f32_e32 v112, v112
	v_rcp_f32_e32 v113, v113
	v_rcp_f32_e32 v114, v114
	v_rcp_f32_e32 v115, v115
	v_mul_f32_e32 v108, 0xbf60028b, v108
	v_mul_f32_e32 v109, 0xbf60028b, v109
	v_mul_f32_e32 v110, 0xbf60028b, v110
	v_mul_f32_e32 v111, 0xbf60028b, v111
	v_cvt_pk_bf16_f32 v116, v112, v113
	v_cvt_pk_bf16_f32 v117, v114, v115
	v_exp_f32_e32 v108, v108
	v_exp_f32_e32 v109, v109
	v_exp_f32_e32 v110, v110
	v_exp_f32_e32 v111, v111
	v_cvt_pk_bf16_f32 v118, v104, v105
	v_cvt_pk_bf16_f32 v119, v106, v107
	global_store_dwordx2 v136, v[116:117], s[44:45]
	global_store_dwordx2 v136, v[118:119], s[46:47]
	global_store_dwordx4 v135, v[108:111], s[54:55]
	v_add_u32_e32 v136, 32, v136
	v_add_u32_e32 v135, 64, v135
	s_waitcnt vmcnt(12)
	s_barrier
	ds_read_b128 v[16:19], v140 offset:0
	ds_read_b128 v[20:23], v140 offset:1024
	ds_read_b128 v[24:27], v140 offset:2048
	ds_read_b128 v[28:31], v140 offset:3072
	ds_read_b128 v[32:35], v140 offset:4096
	ds_read_b128 v[36:39], v140 offset:5120
	ds_read_b128 v[40:43], v140 offset:6144
	ds_read_b128 v[44:47], v140 offset:7168
	s_add_i32 m0, s60, 0x8000
	s_nop 0
	global_load_lds_dwordx4 v138, s[62:63]
	s_add_i32 m0, s60, 0x8400
	s_nop 0
	global_load_lds_dwordx4 v139, s[62:63]
	s_add_u32 s62, s62, s64
	s_addc_u32 s63, s63, 0
	global_load_dwordx4 v[48:51], v134, s[20:21]
	global_load_dwordx4 v[52:55], v134, s[22:23]
	v_add_u32_e32 v134, 64, v134
	s_waitcnt vmcnt(7)
	s_waitcnt lgkmcnt(0)
	v_mfma_f32_16x16x32_bf16 v[96:99], v[16:19], v[184:187], 0
	v_mfma_f32_16x16x32_bf16 v[100:103], v[24:27], v[192:195], 0
	v_mfma_f32_16x16x32_bf16 v[104:107], v[32:35], v[200:203], 0
	v_mfma_f32_16x16x32_bf16 v[96:99], v[20:23], v[188:191], v[96:99]
	v_mfma_f32_16x16x32_bf16 v[100:103], v[28:31], v[196:199], v[100:103]
	v_mfma_f32_16x16x32_bf16 v[104:107], v[36:39], v[204:207], v[104:107]
	v_mfma_f32_16x16x32_bf16 v[104:107], v[40:43], v[208:211], v[104:107]
	v_mfma_f32_16x16x32_bf16 v[104:107], v[44:47], v[212:215], v[104:107]
	s_nop 4
	v_add_f32_e32 v108, v88, v96
	v_add_f32_e32 v109, v89, v97
	v_add_f32_e32 v110, v90, v98
	v_add_f32_e32 v111, v91, v99
	v_add_f32_e32 v112, v92, v100
	v_add_f32_e32 v113, v93, v101
	v_add_f32_e32 v114, v94, v102
	v_add_f32_e32 v115, v95, v103
	v_mul_f32_e32 v108, 0xbfb8aa3b, v108
	v_mul_f32_e32 v109, 0xbfb8aa3b, v109
	v_mul_f32_e32 v110, 0xbfb8aa3b, v110
	v_mul_f32_e32 v111, 0xbfb8aa3b, v111
	v_mul_f32_e32 v112, 0xbfb8aa3b, v112
	v_mul_f32_e32 v113, 0xbfb8aa3b, v113
	v_mul_f32_e32 v114, 0xbfb8aa3b, v114
	v_mul_f32_e32 v115, 0xbfb8aa3b, v115
	v_exp_f32_e32 v108, v108
	v_exp_f32_e32 v109, v109
	v_exp_f32_e32 v110, v110
	v_exp_f32_e32 v111, v111
	v_exp_f32_e32 v112, v112
	v_exp_f32_e32 v113, v113
	v_exp_f32_e32 v114, v114
	v_exp_f32_e32 v115, v115
	v_add_f32_e32 v108, 1.0, v108
	v_add_f32_e32 v109, 1.0, v109
	v_add_f32_e32 v110, 1.0, v110
	v_add_f32_e32 v111, 1.0, v111
	v_add_f32_e32 v112, 1.0, v112
	v_add_f32_e32 v113, 1.0, v113
	v_add_f32_e32 v114, 1.0, v114
	v_add_f32_e32 v115, 1.0, v115
	v_rcp_f32_e32 v108, v108
	v_rcp_f32_e32 v109, v109
	v_rcp_f32_e32 v110, v110
	v_rcp_f32_e32 v111, v111
	v_rcp_f32_e32 v112, v112
	v_rcp_f32_e32 v113, v113
	v_rcp_f32_e32 v114, v114
	v_rcp_f32_e32 v115, v115
	v_mul_f32_e32 v108, 0xbf60028b, v108
	v_mul_f32_e32 v109, 0xbf60028b, v109
	v_mul_f32_e32 v110, 0xbf60028b, v110
	v_mul_f32_e32 v111, 0xbf60028b, v111
	v_cvt_pk_bf16_f32 v116, v112, v113
	v_cvt_pk_bf16_f32 v117, v114, v115
	v_exp_f32_e32 v108, v108
	v_exp_f32_e32 v109, v109
	v_exp_f32_e32 v110, v110
	v_exp_f32_e32 v111, v111
	v_cvt_pk_bf16_f32 v118, v104, v105
	v_cvt_pk_bf16_f32 v119, v106, v107
	global_store_dwordx2 v136, v[116:117], s[44:45]
	global_store_dwordx2 v136, v[118:119], s[46:47]
	global_store_dwordx4 v135, v[108:111], s[54:55]
	v_add_u32_e32 v136, 32, v136
	v_add_u32_e32 v135, 64, v135
	s_waitcnt vmcnt(12)
	s_barrier
; __device__ __forceinline__ unsigned pk2(float lo, float hi) { f32x2 v = {lo, hi}; bf16x2_t b = __builtin_convertvector(v, bf16x2_t); return __builtin_bit_cast(unsigned, b); }
; __device__ __forceinline__ float sigmoidf_(float x) { return frcp(1.f + fexp2(-1.4426950408889634f * x)); }
; __device__ __forceinline__ void phase_lora(const Ctx& p, LAS unsigned char* lds) {
;     ...
;         auto tile = [&](const WF& f, int nt) {
;             f32x4 aw = (f32x4){0.f, 0.f, 0.f, 0.f}, aa = aw, ag = aw;
; #pragma unroll
;             for (int ks = 0; ks < 2; ++ks) { aw = __builtin_amdgcn_mfma_f32_16x16x32_bf16(f.w[ks], bx[ks], aw, 0, 0, 0); aa = __builtin_amdgcn_mfma_f32_16x16x32_bf16(f.a[ks], bx[2 + ks], aa, 0, 0, 0); }
; #pragma unroll
;             for (int ks = 0; ks < 4; ++ks) ag = __builtin_amdgcn_mfma_f32_16x16x32_bf16(f.gq[ks], bx[4 + ks], ag, 0, 0, 0);
;             const int c = nt * 16 + 4 * g;
;             f32x4 dec; float av[4];
; #pragma unroll
;             for (int e = 0; e < 4; ++e) {
;                 const float x = f.w0[e] + aw[e];
;                 const float sp = fmaxf(-x, 0.f) + log1pf(expf(-fabsf(x)));
;                 dec[e] = expf(-expf(-sp - 0.5f));
;                 av[e] = sigmoidf_(f.a0[e] + aa[e]);
;             }
;             *(f32x4*)(DEC + (size_t)row * 512 + c) = dec;
;             *(u32x2*)(AB + (size_t)row * 512 + c) = (u32x2){pk2(av[0], av[1]), pk2(av[2], av[3])};
;             *(u32x2*)(GG + (size_t)row * 512 + c) = (u32x2){pk2(ag[0], ag[1]), pk2(ag[2], ag[3])};
;         };
;         WF fa, fb;
;         ldw(fa, 0);
; #pragma unroll 1
;         for (int nt = 0; nt < 32; nt += 2) {
;             ldw(fb, nt + 1);
;             tile(fa, nt);
;             ldw(fa, (nt + 2) & 31);
;             tile(fb, nt + 1);
	ds_read_b128 v[16:19], v140 offset:16384
	ds_read_b128 v[20:23], v140 offset:17408
	ds_read_b128 v[24:27], v140 offset:18432
	ds_read_b128 v[28:31], v140 offset:19456
	ds_read_b128 v[32:35], v140 offset:20480
	ds_read_b128 v[36:39], v140 offset:21504
	ds_read_b128 v[40:43], v140 offset:22528
	ds_read_b128 v[44:47], v140 offset:23552
	s_add_i32 m0, s60, 0x0
	s_nop 0
	global_load_lds_dwordx4 v138, s[62:63]
	s_add_i32 m0, s60, 0x400
	s_nop 0
	global_load_lds_dwordx4 v139, s[62:63]
	s_add_u32 s62, s62, s64
	s_addc_u32 s63, s63, 0
	global_load_dwordx4 v[88:91], v134, s[20:21]
	global_load_dwordx4 v[92:95], v134, s[22:23]
	v_add_u32_e32 v134, 64, v134
	s_waitcnt vmcnt(7)
	s_waitcnt lgkmcnt(0)
	v_mfma_f32_16x16x32_bf16 v[96:99], v[16:19], v[184:187], 0
	v_mfma_f32_16x16x32_bf16 v[100:103], v[24:27], v[192:195], 0
	v_mfma_f32_16x16x32_bf16 v[104:107], v[32:35], v[200:203], 0
	v_mfma_f32_16x16x32_bf16 v[96:99], v[20:23], v[188:191], v[96:99]
	v_mfma_f32_16x16x32_bf16 v[100:103], v[28:31], v[196:199], v[100:103]
	v_mfma_f32_16x16x32_bf16 v[104:107], v[36:39], v[204:207], v[104:107]
	v_mfma_f32_16x16x32_bf16 v[104:107], v[40:43], v[208:211], v[104:107]
	v_mfma_f32_16x16x32_bf16 v[104:107], v[44:47], v[212:215], v[104:107]
	s_nop 4
	v_add_f32_e32 v108, v48, v96
	v_add_f32_e32 v109, v49, v97
	v_add_f32_e32 v110, v50, v98
	v_add_f32_e32 v111, v51, v99
	v_add_f32_e32 v112, v52, v100
	v_add_f32_e32 v113, v53, v101
	v_add_f32_e32 v114, v54, v102
	v_add_f32_e32 v115, v55, v103
	v_mul_f32_e32 v108, 0xbfb8aa3b, v108
	v_mul_f32_e32 v109, 0xbfb8aa3b, v109
	v_mul_f32_e32 v110, 0xbfb8aa3b, v110
	v_mul_f32_e32 v111, 0xbfb8aa3b, v111
	v_mul_f32_e32 v112, 0xbfb8aa3b, v112
	v_mul_f32_e32 v113, 0xbfb8aa3b, v113
	v_mul_f32_e32 v114, 0xbfb8aa3b, v114
	v_mul_f32_e32 v115, 0xbfb8aa3b, v115
	v_exp_f32_e32 v108, v108
	v_exp_f32_e32 v109, v109
	v_exp_f32_e32 v110, v110
	v_exp_f32_e32 v111, v111
	v_exp_f32_e32 v112, v112
	v_exp_f32_e32 v113, v113
	v_exp_f32_e32 v114, v114
	v_exp_f32_e32 v115, v115
	v_add_f32_e32 v108, 1.0, v108
	v_add_f32_e32 v109, 1.0, v109
	v_add_f32_e32 v110, 1.0, v110
	v_add_f32_e32 v111, 1.0, v111
	v_add_f32_e32 v112, 1.0, v112
	v_add_f32_e32 v113, 1.0, v113
	v_add_f32_e32 v114, 1.0, v114
	v_add_f32_e32 v115, 1.0, v115
	v_rcp_f32_e32 v108, v108
	v_rcp_f32_e32 v109, v109
	v_rcp_f32_e32 v110, v110
	v_rcp_f32_e32 v111, v111
	v_rcp_f32_e32 v112, v112
	v_rcp_f32_e32 v113, v113
	v_rcp_f32_e32 v114, v114
	v_rcp_f32_e32 v115, v115
	v_mul_f32_e32 v108, 0xbf60028b, v108
	v_mul_f32_e32 v109, 0xbf60028b, v109
	v_mul_f32_e32 v110, 0xbf60028b, v110
	v_mul_f32_e32 v111, 0xbf60028b, v111
	v_cvt_pk_bf16_f32 v116, v112, v113
	v_cvt_pk_bf16_f32 v117, v114, v115
	v_exp_f32_e32 v108, v108
	v_exp_f32_e32 v109, v109
	v_exp_f32_e32 v110, v110
	v_exp_f32_e32 v111, v111
	v_cvt_pk_bf16_f32 v118, v104, v105
	v_cvt_pk_bf16_f32 v119, v106, v107
	global_store_dwordx2 v136, v[116:117], s[44:45]
	global_store_dwordx2 v136, v[118:119], s[46:47]
	global_store_dwordx4 v135, v[108:111], s[54:55]
	v_add_u32_e32 v136, 32, v136
	v_add_u32_e32 v135, 64, v135
	s_waitcnt vmcnt(12)
	s_barrier
	ds_read_b128 v[16:19], v140 offset:32768
	ds_read_b128 v[20:23], v140 offset:33792
	ds_read_b128 v[24:27], v140 offset:34816
	ds_read_b128 v[28:31], v140 offset:35840
	ds_read_b128 v[32:35], v140 offset:36864
	ds_read_b128 v[36:39], v140 offset:37888
	ds_read_b128 v[40:43], v140 offset:38912
	ds_read_b128 v[44:47], v140 offset:39936
	s_add_i32 m0, s60, 0x4000
	s_nop 0
	global_load_lds_dwordx4 v138, s[62:63]
	s_add_i32 m0, s60, 0x4400
	s_nop 0
	global_load_lds_dwordx4 v139, s[62:63]
	s_add_u32 s62, s62, s64
	s_addc_u32 s63, s63, 0
	global_load_dwordx4 v[48:51], v134, s[20:21]
	global_load_dwordx4 v[52:55], v134, s[22:23]
	v_add_u32_e32 v134, 64, v134
	s_waitcnt vmcnt(7)
	s_waitcnt lgkmcnt(0)
	v_mfma_f32_16x16x32_bf16 v[96:99], v[16:19], v[184:187], 0
	v_mfma_f32_16x16x32_bf16 v[100:103], v[24:27], v[192:195], 0
	v_mfma_f32_16x16x32_bf16 v[104:107], v[32:35], v[200:203], 0
	v_mfma_f32_16x16x32_bf16 v[96:99], v[20:23], v[188:191], v[96:99]
	v_mfma_f32_16x16x32_bf16 v[100:103], v[28:31], v[196:199], v[100:103]
	v_mfma_f32_16x16x32_bf16 v[104:107], v[36:39], v[204:207], v[104:107]
	v_mfma_f32_16x16x32_bf16 v[104:107], v[40:43], v[208:211], v[104:107]
	v_mfma_f32_16x16x32_bf16 v[104:107], v[44:47], v[212:215], v[104:107]
	s_nop 4
	v_add_f32_e32 v108, v88, v96
	v_add_f32_e32 v109, v89, v97
	v_add_f32_e32 v110, v90, v98
	v_add_f32_e32 v111, v91, v99
	v_add_f32_e32 v112, v92, v100
	v_add_f32_e32 v113, v93, v101
	v_add_f32_e32 v114, v94, v102
	v_add_f32_e32 v115, v95, v103
	v_mul_f32_e32 v108, 0xbfb8aa3b, v108
	v_mul_f32_e32 v109, 0xbfb8aa3b, v109
	v_mul_f32_e32 v110, 0xbfb8aa3b, v110
	v_mul_f32_e32 v111, 0xbfb8aa3b, v111
	v_mul_f32_e32 v112, 0xbfb8aa3b, v112
	v_mul_f32_e32 v113, 0xbfb8aa3b, v113
	v_mul_f32_e32 v114, 0xbfb8aa3b, v114
	v_mul_f32_e32 v115, 0xbfb8aa3b, v115
	v_exp_f32_e32 v108, v108
	v_exp_f32_e32 v109, v109
	v_exp_f32_e32 v110, v110
	v_exp_f32_e32 v111, v111
	v_exp_f32_e32 v112, v112
	v_exp_f32_e32 v113, v113
	v_exp_f32_e32 v114, v114
	v_exp_f32_e32 v115, v115
	v_add_f32_e32 v108, 1.0, v108
	v_add_f32_e32 v109, 1.0, v109
	v_add_f32_e32 v110, 1.0, v110
	v_add_f32_e32 v111, 1.0, v111
	v_add_f32_e32 v112, 1.0, v112
	v_add_f32_e32 v113, 1.0, v113
	v_add_f32_e32 v114, 1.0, v114
	v_add_f32_e32 v115, 1.0, v115
	v_rcp_f32_e32 v108, v108
	v_rcp_f32_e32 v109, v109
	v_rcp_f32_e32 v110, v110
	v_rcp_f32_e32 v111, v111
	v_rcp_f32_e32 v112, v112
	v_rcp_f32_e32 v113, v113
	v_rcp_f32_e32 v114, v114
	v_rcp_f32_e32 v115, v115
	v_mul_f32_e32 v108, 0xbf60028b, v108
	v_mul_f32_e32 v109, 0xbf60028b, v109
	v_mul_f32_e32 v110, 0xbf60028b, v110
	v_mul_f32_e32 v111, 0xbf60028b, v111
	v_cvt_pk_bf16_f32 v116, v112, v113
	v_cvt_pk_bf16_f32 v117, v114, v115
	v_exp_f32_e32 v108, v108
	v_exp_f32_e32 v109, v109
	v_exp_f32_e32 v110, v110
	v_exp_f32_e32 v111, v111
	v_cvt_pk_bf16_f32 v118, v104, v105
	v_cvt_pk_bf16_f32 v119, v106, v107
	global_store_dwordx2 v136, v[116:117], s[44:45]
	global_store_dwordx2 v136, v[118:119], s[46:47]
	global_store_dwordx4 v135, v[108:111], s[54:55]
	v_add_u32_e32 v136, 32, v136
	v_add_u32_e32 v135, 64, v135
	s_waitcnt vmcnt(12)
	s_barrier
; __device__ __forceinline__ unsigned pk2(float lo, float hi) { f32x2 v = {lo, hi}; bf16x2_t b = __builtin_convertvector(v, bf16x2_t); return __builtin_bit_cast(unsigned, b); }
; __device__ __forceinline__ float sigmoidf_(float x) { return frcp(1.f + fexp2(-1.4426950408889634f * x)); }
;     __device__ __forceinline__ const float* in(int i) const { return (const float*)ptr(i); }
; __device__ __forceinline__ void phase_lora(const Ctx& p, LAS unsigned char* lds) {
;     ...
;         auto ldw = [&](WF& f, int nt) {
;             const int n = nt * 16 + q, c = nt * 16 + 4 * g;
; #pragma unroll
;             for (int ks = 0; ks < 2; ++ks) { f.w[ks] = *(const bf16x8*)(w2T + n * 64 + ks * 32 + 8 * g); f.a[ks] = *(const bf16x8*)(a2T + n * 64 + ks * 32 + 8 * g); }
; #pragma unroll
;             for (int ks = 0; ks < 4; ++ks) f.gq[ks] = *(const bf16x8*)(g2T + n * 128 + ks * 32 + 8 * g);
;             f.w0 = *(const f32x4*)(p.in(18) + c); f.a0 = *(const f32x4*)(p.in(20) + c);
;         };
;         auto tile = [&](const WF& f, int nt) {
;             f32x4 aw = (f32x4){0.f, 0.f, 0.f, 0.f}, aa = aw, ag = aw;
; #pragma unroll
;             for (int ks = 0; ks < 2; ++ks) { aw = __builtin_amdgcn_mfma_f32_16x16x32_bf16(f.w[ks], bx[ks], aw, 0, 0, 0); aa = __builtin_amdgcn_mfma_f32_16x16x32_bf16(f.a[ks], bx[2 + ks], aa, 0, 0, 0); }
; #pragma unroll
;             for (int ks = 0; ks < 4; ++ks) ag = __builtin_amdgcn_mfma_f32_16x16x32_bf16(f.gq[ks], bx[4 + ks], ag, 0, 0, 0);
;             const int c = nt * 16 + 4 * g;
;             f32x4 dec; float av[4];
; #pragma unroll
;             for (int e = 0; e < 4; ++e) {
;                 const float x = f.w0[e] + aw[e];
;                 const float sp = fmaxf(-x, 0.f) + log1pf(expf(-fabsf(x)));
;                 dec[e] = expf(-expf(-sp - 0.5f));
;                 av[e] = sigmoidf_(f.a0[e] + aa[e]);
;             }
;             *(f32x4*)(DEC + (size_t)row * 512 + c) = dec;
;             *(u32x2*)(AB + (size_t)row * 512 + c) = (u32x2){pk2(av[0], av[1]), pk2(av[2], av[3])};
;             *(u32x2*)(GG + (size_t)row * 512 + c) = (u32x2){pk2(ag[0], ag[1]), pk2(ag[2], ag[3])};
;         };
	ds_read_b128 v[16:19], v140 offset:0
	ds_read_b128 v[20:23], v140 offset:1024
	ds_read_b128 v[24:27], v140 offset:2048
	ds_read_b128 v[28:31], v140 offset:3072
	ds_read_b128 v[32:35], v140 offset:4096
	ds_read_b128 v[36:39], v140 offset:5120
	ds_read_b128 v[40:43], v140 offset:6144
	ds_read_b128 v[44:47], v140 offset:7168
	s_add_i32 m0, s60, 0x8000
	s_nop 0
	global_load_lds_dwordx4 v138, s[62:63]
	s_add_i32 m0, s60, 0x8400
	s_nop 0
	global_load_lds_dwordx4 v139, s[62:63]
	s_add_u32 s62, s62, s64
	s_addc_u32 s63, s63, 0
	global_load_dwordx4 v[88:91], v134, s[20:21]
	global_load_dwordx4 v[92:95], v134, s[22:23]
	v_add_u32_e32 v134, 64, v134
	s_waitcnt vmcnt(7)
	s_waitcnt lgkmcnt(0)
	v_mfma_f32_16x16x32_bf16 v[96:99], v[16:19], v[184:187], 0
	v_mfma_f32_16x16x32_bf16 v[100:103], v[24:27], v[192:195], 0
	v_mfma_f32_16x16x32_bf16 v[104:107], v[32:35], v[200:203], 0
	v_mfma_f32_16x16x32_bf16 v[96:99], v[20:23], v[188:191], v[96:99]
	v_mfma_f32_16x16x32_bf16 v[100:103], v[28:31], v[196:199], v[100:103]
	v_mfma_f32_16x16x32_bf16 v[104:107], v[36:39], v[204:207], v[104:107]
	v_mfma_f32_16x16x32_bf16 v[104:107], v[40:43], v[208:211], v[104:107]
	v_mfma_f32_16x16x32_bf16 v[104:107], v[44:47], v[212:215], v[104:107]
	s_nop 4
	v_add_f32_e32 v108, v48, v96
	v_add_f32_e32 v109, v49, v97
	v_add_f32_e32 v110, v50, v98
	v_add_f32_e32 v111, v51, v99
	v_add_f32_e32 v112, v52, v100
	v_add_f32_e32 v113, v53, v101
	v_add_f32_e32 v114, v54, v102
	v_add_f32_e32 v115, v55, v103
	v_mul_f32_e32 v108, 0xbfb8aa3b, v108
	v_mul_f32_e32 v109, 0xbfb8aa3b, v109
	v_mul_f32_e32 v110, 0xbfb8aa3b, v110
	v_mul_f32_e32 v111, 0xbfb8aa3b, v111
	v_mul_f32_e32 v112, 0xbfb8aa3b, v112
	v_mul_f32_e32 v113, 0xbfb8aa3b, v113
	v_mul_f32_e32 v114, 0xbfb8aa3b, v114
	v_mul_f32_e32 v115, 0xbfb8aa3b, v115
	v_exp_f32_e32 v108, v108
	v_exp_f32_e32 v109, v109
	v_exp_f32_e32 v110, v110
	v_exp_f32_e32 v111, v111
	v_exp_f32_e32 v112, v112
	v_exp_f32_e32 v113, v113
	v_exp_f32_e32 v114, v114
	v_exp_f32_e32 v115, v115
	v_add_f32_e32 v108, 1.0, v108
	v_add_f32_e32 v109, 1.0, v109
	v_add_f32_e32 v110, 1.0, v110
	v_add_f32_e32 v111, 1.0, v111
	v_add_f32_e32 v112, 1.0, v112
	v_add_f32_e32 v113, 1.0, v113
	v_add_f32_e32 v114, 1.0, v114
	v_add_f32_e32 v115, 1.0, v115
	v_rcp_f32_e32 v108, v108
	v_rcp_f32_e32 v109, v109
	v_rcp_f32_e32 v110, v110
	v_rcp_f32_e32 v111, v111
	v_rcp_f32_e32 v112, v112
	v_rcp_f32_e32 v113, v113
	v_rcp_f32_e32 v114, v114
	v_rcp_f32_e32 v115, v115
	v_mul_f32_e32 v108, 0xbf60028b, v108
	v_mul_f32_e32 v109, 0xbf60028b, v109
	v_mul_f32_e32 v110, 0xbf60028b, v110
	v_mul_f32_e32 v111, 0xbf60028b, v111
	v_cvt_pk_bf16_f32 v116, v112, v113
	v_cvt_pk_bf16_f32 v117, v114, v115
	v_exp_f32_e32 v108, v108
	v_exp_f32_e32 v109, v109
	v_exp_f32_e32 v110, v110
	v_exp_f32_e32 v111, v111
	v_cvt_pk_bf16_f32 v118, v104, v105
	v_cvt_pk_bf16_f32 v119, v106, v107
	global_store_dwordx2 v136, v[116:117], s[44:45]
	global_store_dwordx2 v136, v[118:119], s[46:47]
	global_store_dwordx4 v135, v[108:111], s[54:55]
	v_add_u32_e32 v136, 32, v136
	v_add_u32_e32 v135, 64, v135
	s_waitcnt vmcnt(12)
	s_barrier
	ds_read_b128 v[16:19], v140 offset:16384
	ds_read_b128 v[20:23], v140 offset:17408
	ds_read_b128 v[24:27], v140 offset:18432
	ds_read_b128 v[28:31], v140 offset:19456
	ds_read_b128 v[32:35], v140 offset:20480
	ds_read_b128 v[36:39], v140 offset:21504
	ds_read_b128 v[40:43], v140 offset:22528
	ds_read_b128 v[44:47], v140 offset:23552
	s_add_i32 m0, s60, 0x0
	s_nop 0
	global_load_lds_dwordx4 v138, s[62:63]
	s_add_i32 m0, s60, 0x400
	s_nop 0
	global_load_lds_dwordx4 v139, s[62:63]
	s_add_u32 s62, s62, s64
	s_addc_u32 s63, s63, 0
	global_load_dwordx4 v[48:51], v134, s[20:21]
	global_load_dwordx4 v[52:55], v134, s[22:23]
	v_add_u32_e32 v134, 64, v134
	s_waitcnt vmcnt(7)
	s_waitcnt lgkmcnt(0)
	v_mfma_f32_16x16x32_bf16 v[96:99], v[16:19], v[184:187], 0
	v_mfma_f32_16x16x32_bf16 v[100:103], v[24:27], v[192:195], 0
	v_mfma_f32_16x16x32_bf16 v[104:107], v[32:35], v[200:203], 0
	v_mfma_f32_16x16x32_bf16 v[96:99], v[20:23], v[188:191], v[96:99]
	v_mfma_f32_16x16x32_bf16 v[100:103], v[28:31], v[196:199], v[100:103]
	v_mfma_f32_16x16x32_bf16 v[104:107], v[36:39], v[204:207], v[104:107]
	v_mfma_f32_16x16x32_bf16 v[104:107], v[40:43], v[208:211], v[104:107]
	v_mfma_f32_16x16x32_bf16 v[104:107], v[44:47], v[212:215], v[104:107]
	s_nop 4
	v_add_f32_e32 v108, v88, v96
	v_add_f32_e32 v109, v89, v97
	v_add_f32_e32 v110, v90, v98
	v_add_f32_e32 v111, v91, v99
	v_add_f32_e32 v112, v92, v100
	v_add_f32_e32 v113, v93, v101
	v_add_f32_e32 v114, v94, v102
	v_add_f32_e32 v115, v95, v103
	v_mul_f32_e32 v108, 0xbfb8aa3b, v108
	v_mul_f32_e32 v109, 0xbfb8aa3b, v109
	v_mul_f32_e32 v110, 0xbfb8aa3b, v110
	v_mul_f32_e32 v111, 0xbfb8aa3b, v111
	v_mul_f32_e32 v112, 0xbfb8aa3b, v112
	v_mul_f32_e32 v113, 0xbfb8aa3b, v113
	v_mul_f32_e32 v114, 0xbfb8aa3b, v114
	v_mul_f32_e32 v115, 0xbfb8aa3b, v115
	v_exp_f32_e32 v108, v108
	v_exp_f32_e32 v109, v109
	v_exp_f32_e32 v110, v110
	v_exp_f32_e32 v111, v111
	v_exp_f32_e32 v112, v112
	v_exp_f32_e32 v113, v113
	v_exp_f32_e32 v114, v114
	v_exp_f32_e32 v115, v115
	v_add_f32_e32 v108, 1.0, v108
	v_add_f32_e32 v109, 1.0, v109
	v_add_f32_e32 v110, 1.0, v110
	v_add_f32_e32 v111, 1.0, v111
	v_add_f32_e32 v112, 1.0, v112
	v_add_f32_e32 v113, 1.0, v113
	v_add_f32_e32 v114, 1.0, v114
	v_add_f32_e32 v115, 1.0, v115
	v_rcp_f32_e32 v108, v108
	v_rcp_f32_e32 v109, v109
	v_rcp_f32_e32 v110, v110
	v_rcp_f32_e32 v111, v111
	v_rcp_f32_e32 v112, v112
	v_rcp_f32_e32 v113, v113
	v_rcp_f32_e32 v114, v114
	v_rcp_f32_e32 v115, v115
	v_mul_f32_e32 v108, 0xbf60028b, v108
	v_mul_f32_e32 v109, 0xbf60028b, v109
	v_mul_f32_e32 v110, 0xbf60028b, v110
	v_mul_f32_e32 v111, 0xbf60028b, v111
	v_cvt_pk_bf16_f32 v116, v112, v113
	v_cvt_pk_bf16_f32 v117, v114, v115
	v_exp_f32_e32 v108, v108
	v_exp_f32_e32 v109, v109
	v_exp_f32_e32 v110, v110
	v_exp_f32_e32 v111, v111
	v_cvt_pk_bf16_f32 v118, v104, v105
	v_cvt_pk_bf16_f32 v119, v106, v107
	global_store_dwordx2 v136, v[116:117], s[44:45]
	global_store_dwordx2 v136, v[118:119], s[46:47]
	global_store_dwordx4 v135, v[108:111], s[54:55]
	v_add_u32_e32 v136, 32, v136
	v_add_u32_e32 v135, 64, v135
	s_waitcnt vmcnt(12)
	s_barrier
; __device__ __forceinline__ unsigned pk2(float lo, float hi) { f32x2 v = {lo, hi}; bf16x2_t b = __builtin_convertvector(v, bf16x2_t); return __builtin_bit_cast(unsigned, b); }
; __device__ __forceinline__ float sigmoidf_(float x) { return frcp(1.f + fexp2(-1.4426950408889634f * x)); }
; __device__ __forceinline__ void phase_lora(const Ctx& p, LAS unsigned char* lds) {
;     ...
;         auto ldw = [&](WF& f, int nt) {
;             const int n = nt * 16 + q, c = nt * 16 + 4 * g;
; #pragma unroll
;             for (int ks = 0; ks < 2; ++ks) { f.w[ks] = *(const bf16x8*)(w2T + n * 64 + ks * 32 + 8 * g); f.a[ks] = *(const bf16x8*)(a2T + n * 64 + ks * 32 + 8 * g); }
; #pragma unroll
;             for (int ks = 0; ks < 4; ++ks) f.gq[ks] = *(const bf16x8*)(g2T + n * 128 + ks * 32 + 8 * g);
;             f.w0 = *(const f32x4*)(p.in(18) + c); f.a0 = *(const f32x4*)(p.in(20) + c);
;         };
;         auto tile = [&](const WF& f, int nt) {
;             f32x4 aw = (f32x4){0.f, 0.f, 0.f, 0.f}, aa = aw, ag = aw;
; #pragma unroll
;             for (int ks = 0; ks < 2; ++ks) { aw = __builtin_amdgcn_mfma_f32_16x16x32_bf16(f.w[ks], bx[ks], aw, 0, 0, 0); aa = __builtin_amdgcn_mfma_f32_16x16x32_bf16(f.a[ks], bx[2 + ks], aa, 0, 0, 0); }
; #pragma unroll
;             for (int ks = 0; ks < 4; ++ks) ag = __builtin_amdgcn_mfma_f32_16x16x32_bf16(f.gq[ks], bx[4 + ks], ag, 0, 0, 0);
;             const int c = nt * 16 + 4 * g;
;             f32x4 dec; float av[4];
; #pragma unroll
;             for (int e = 0; e < 4; ++e) {
;                 const float x = f.w0[e] + aw[e];
;                 const float sp = fmaxf(-x, 0.f) + log1pf(expf(-fabsf(x)));
;                 dec[e] = expf(-expf(-sp - 0.5f));
;                 av[e] = sigmoidf_(f.a0[e] + aa[e]);
;             }
;             *(f32x4*)(DEC + (size_t)row * 512 + c) = dec;
;             *(u32x2*)(AB + (size_t)row * 512 + c) = (u32x2){pk2(av[0], av[1]), pk2(av[2], av[3])};
;             *(u32x2*)(GG + (size_t)row * 512 + c) = (u32x2){pk2(ag[0], ag[1]), pk2(ag[2], ag[3])};
;         };
;         WF fa, fb;
;         ldw(fa, 0);
; #pragma unroll 1
;         for (int nt = 0; nt < 32; nt += 2) {
;             ldw(fb, nt + 1);
;             tile(fa, nt);
;             ldw(fa, (nt + 2) & 31);
;             tile(fb, nt + 1);
;         }
;         asm volatile("s_waitcnt lgkmcnt(0)" ::: "memory");
;     }
	ds_read_b128 v[16:19], v140 offset:32768
	ds_read_b128 v[20:23], v140 offset:33792
	ds_read_b128 v[24:27], v140 offset:34816
	ds_read_b128 v[28:31], v140 offset:35840
	ds_read_b128 v[32:35], v140 offset:36864
	ds_read_b128 v[36:39], v140 offset:37888
	ds_read_b128 v[40:43], v140 offset:38912
	ds_read_b128 v[44:47], v140 offset:39936
	global_load_dwordx4 v[88:91], v134, s[20:21]
	global_load_dwordx4 v[92:95], v134, s[22:23]
	v_add_u32_e32 v134, 64, v134
	s_waitcnt vmcnt(5)
	s_waitcnt lgkmcnt(0)
	v_mfma_f32_16x16x32_bf16 v[96:99], v[16:19], v[184:187], 0
	v_mfma_f32_16x16x32_bf16 v[100:103], v[24:27], v[192:195], 0
	v_mfma_f32_16x16x32_bf16 v[104:107], v[32:35], v[200:203], 0
	v_mfma_f32_16x16x32_bf16 v[96:99], v[20:23], v[188:191], v[96:99]
	v_mfma_f32_16x16x32_bf16 v[100:103], v[28:31], v[196:199], v[100:103]
	v_mfma_f32_16x16x32_bf16 v[104:107], v[36:39], v[204:207], v[104:107]
	v_mfma_f32_16x16x32_bf16 v[104:107], v[40:43], v[208:211], v[104:107]
	v_mfma_f32_16x16x32_bf16 v[104:107], v[44:47], v[212:215], v[104:107]
	s_nop 4
	v_add_f32_e32 v108, v48, v96
	v_add_f32_e32 v109, v49, v97
	v_add_f32_e32 v110, v50, v98
	v_add_f32_e32 v111, v51, v99
	v_add_f32_e32 v112, v52, v100
	v_add_f32_e32 v113, v53, v101
	v_add_f32_e32 v114, v54, v102
	v_add_f32_e32 v115, v55, v103
	v_mul_f32_e32 v108, 0xbfb8aa3b, v108
	v_mul_f32_e32 v109, 0xbfb8aa3b, v109
	v_mul_f32_e32 v110, 0xbfb8aa3b, v110
	v_mul_f32_e32 v111, 0xbfb8aa3b, v111
	v_mul_f32_e32 v112, 0xbfb8aa3b, v112
	v_mul_f32_e32 v113, 0xbfb8aa3b, v113
	v_mul_f32_e32 v114, 0xbfb8aa3b, v114
	v_mul_f32_e32 v115, 0xbfb8aa3b, v115
	v_exp_f32_e32 v108, v108
	v_exp_f32_e32 v109, v109
	v_exp_f32_e32 v110, v110
	v_exp_f32_e32 v111, v111
	v_exp_f32_e32 v112, v112
	v_exp_f32_e32 v113, v113
	v_exp_f32_e32 v114, v114
	v_exp_f32_e32 v115, v115
	v_add_f32_e32 v108, 1.0, v108
	v_add_f32_e32 v109, 1.0, v109
	v_add_f32_e32 v110, 1.0, v110
	v_add_f32_e32 v111, 1.0, v111
	v_add_f32_e32 v112, 1.0, v112
	v_add_f32_e32 v113, 1.0, v113
	v_add_f32_e32 v114, 1.0, v114
	v_add_f32_e32 v115, 1.0, v115
	v_rcp_f32_e32 v108, v108
	v_rcp_f32_e32 v109, v109
	v_rcp_f32_e32 v110, v110
	v_rcp_f32_e32 v111, v111
	v_rcp_f32_e32 v112, v112
	v_rcp_f32_e32 v113, v113
	v_rcp_f32_e32 v114, v114
	v_rcp_f32_e32 v115, v115
	v_mul_f32_e32 v108, 0xbf60028b, v108
	v_mul_f32_e32 v109, 0xbf60028b, v109
	v_mul_f32_e32 v110, 0xbf60028b, v110
	v_mul_f32_e32 v111, 0xbf60028b, v111
	v_cvt_pk_bf16_f32 v116, v112, v113
	v_cvt_pk_bf16_f32 v117, v114, v115
	v_exp_f32_e32 v108, v108
	v_exp_f32_e32 v109, v109
	v_exp_f32_e32 v110, v110
	v_exp_f32_e32 v111, v111
	v_cvt_pk_bf16_f32 v118, v104, v105
	v_cvt_pk_bf16_f32 v119, v106, v107
	global_store_dwordx2 v136, v[116:117], s[44:45]
	global_store_dwordx2 v136, v[118:119], s[46:47]
	global_store_dwordx4 v135, v[108:111], s[54:55]
	v_add_u32_e32 v136, 32, v136
	v_add_u32_e32 v135, 64, v135
	s_waitcnt vmcnt(10)
	s_barrier
	ds_read_b128 v[16:19], v140 offset:0
	ds_read_b128 v[20:23], v140 offset:1024
	ds_read_b128 v[24:27], v140 offset:2048
	ds_read_b128 v[28:31], v140 offset:3072
	ds_read_b128 v[32:35], v140 offset:4096
	ds_read_b128 v[36:39], v140 offset:5120
	ds_read_b128 v[40:43], v140 offset:6144
	ds_read_b128 v[44:47], v140 offset:7168
	s_waitcnt vmcnt(3)
	s_waitcnt lgkmcnt(0)
	v_mfma_f32_16x16x32_bf16 v[96:99], v[16:19], v[184:187], 0
	v_mfma_f32_16x16x32_bf16 v[100:103], v[24:27], v[192:195], 0
	v_mfma_f32_16x16x32_bf16 v[104:107], v[32:35], v[200:203], 0
	v_mfma_f32_16x16x32_bf16 v[96:99], v[20:23], v[188:191], v[96:99]
	v_mfma_f32_16x16x32_bf16 v[100:103], v[28:31], v[196:199], v[100:103]
	v_mfma_f32_16x16x32_bf16 v[104:107], v[36:39], v[204:207], v[104:107]
	v_mfma_f32_16x16x32_bf16 v[104:107], v[40:43], v[208:211], v[104:107]
	v_mfma_f32_16x16x32_bf16 v[104:107], v[44:47], v[212:215], v[104:107]
	s_nop 4
	v_add_f32_e32 v108, v88, v96
	v_add_f32_e32 v109, v89, v97
	v_add_f32_e32 v110, v90, v98
	v_add_f32_e32 v111, v91, v99
	v_add_f32_e32 v112, v92, v100
	v_add_f32_e32 v113, v93, v101
	v_add_f32_e32 v114, v94, v102
	v_add_f32_e32 v115, v95, v103
	v_mul_f32_e32 v108, 0xbfb8aa3b, v108
	v_mul_f32_e32 v109, 0xbfb8aa3b, v109
	v_mul_f32_e32 v110, 0xbfb8aa3b, v110
	v_mul_f32_e32 v111, 0xbfb8aa3b, v111
	v_mul_f32_e32 v112, 0xbfb8aa3b, v112
	v_mul_f32_e32 v113, 0xbfb8aa3b, v113
	v_mul_f32_e32 v114, 0xbfb8aa3b, v114
	v_mul_f32_e32 v115, 0xbfb8aa3b, v115
	v_exp_f32_e32 v108, v108
	v_exp_f32_e32 v109, v109
	v_exp_f32_e32 v110, v110
	v_exp_f32_e32 v111, v111
	v_exp_f32_e32 v112, v112
	v_exp_f32_e32 v113, v113
	v_exp_f32_e32 v114, v114
	v_exp_f32_e32 v115, v115
	v_add_f32_e32 v108, 1.0, v108
	v_add_f32_e32 v109, 1.0, v109
	v_add_f32_e32 v110, 1.0, v110
	v_add_f32_e32 v111, 1.0, v111
	v_add_f32_e32 v112, 1.0, v112
	v_add_f32_e32 v113, 1.0, v113
	v_add_f32_e32 v114, 1.0, v114
	v_add_f32_e32 v115, 1.0, v115
	v_rcp_f32_e32 v108, v108
	v_rcp_f32_e32 v109, v109
	v_rcp_f32_e32 v110, v110
	v_rcp_f32_e32 v111, v111
	v_rcp_f32_e32 v112, v112
	v_rcp_f32_e32 v113, v113
	v_rcp_f32_e32 v114, v114
	v_rcp_f32_e32 v115, v115
	v_mul_f32_e32 v108, 0xbf60028b, v108
	v_mul_f32_e32 v109, 0xbf60028b, v109
	v_mul_f32_e32 v110, 0xbf60028b, v110
	v_mul_f32_e32 v111, 0xbf60028b, v111
	v_cvt_pk_bf16_f32 v116, v112, v113
	v_cvt_pk_bf16_f32 v117, v114, v115
	v_exp_f32_e32 v108, v108
	v_exp_f32_e32 v109, v109
	v_exp_f32_e32 v110, v110
	v_exp_f32_e32 v111, v111
	v_cvt_pk_bf16_f32 v118, v104, v105
	v_cvt_pk_bf16_f32 v119, v106, v107
	global_store_dwordx2 v136, v[116:117], s[44:45]
	global_store_dwordx2 v136, v[118:119], s[46:47]
	global_store_dwordx4 v135, v[108:111], s[54:55]
	v_add_u32_e32 v136, 32, v136
	v_add_u32_e32 v135, 64, v135
	s_cmp_lt_u32 s28, 32
	s_cbranch_scc0 .Llora_done
	s_mov_b32 s57, 1
	s_lshr_b32 s2, s28, 2
	s_add_i32 s26, s2, 0x400
	s_branch .Llora_item
